# combination: attention with moved barriers + single fp32 ops, pass-1 row loads through LDS, rotary-row prefetch
# baseline (speedup 1.0000x reference)
.Latt_unit:
	s_mov_b32 s33, s12
	s_mov_b32 s34, s15
	s_mov_b32 s35, s16
	s_mov_b32 s36, s17
	s_mov_b32 s38, s14
	s_mov_b32 s39, s13
	s_mov_b32 s24, s20
	s_mov_b32 s25, s21
	s_mov_b32 s26, s22
	s_mov_b32 s27, s23
	s_mov_b32 s40, s42
	s_mov_b32 s41, s43
	v_mov_b32_e32 v173, v176
	v_mov_b32_e32 v174, v177
	s_lshr_b32 s44, s33, 0
	s_lshr_b32 s2, s0, 2
	s_lshl_b32 s2, s2, 5
	s_lshr_b32 s3, s15, 2
	s_add_i32 s42, s3, s2
	s_and_b32 s43, s0, 3
	s_waitcnt vmcnt(4)
	ds_write_b128 v253, v[0:3]
	ds_write_b128 v253, v[4:7] offset:1152
	ds_write_b128 v253, v[8:11] offset:2304
	ds_write_b128 v253, v[12:15] offset:3456
	ds_write_b128 v253, v[16:19] offset:4608
	ds_write_b128 v253, v[20:23] offset:5760
	ds_write_b128 v253, v[24:27] offset:55296
	ds_write_b128 v253, v[28:31] offset:56448
	ds_write_b128 v253, v[32:35] offset:57600
	ds_write_b128 v253, v[36:39] offset:58752
	ds_write_b128 v253, v[40:43] offset:59904
	ds_write_b128 v253, v[44:47] offset:61056
	s_lshl_b32 s2, s0, 12
	s_add_i32 s2, s2, 0x1b500
	v_and_b32_e32 v141, 63, v145
	v_lshl_add_u32 v141, v141, 4, s2
	ds_write_b128 v141, v[48:51]
	ds_write_b128 v141, v[52:55] offset:1024
	ds_write_b128 v141, v[56:59] offset:2048
	ds_write_b128 v141, v[60:63] offset:3072
	s_waitcnt lgkmcnt(0)
	s_barrier
	v_add_u32_e32 v134, s42, v160
	v_lshlrev_b32_e32 v134, 2, v134
	v_add_u32_e32 v134, s43, v134
	v_subrev_u32_e32 v135, s15, v134
	v_lshrrev_b32_e32 v136, 4, v135
	v_add_u32_e32 v136, v136, v135
	v_mad_u32_u24 v176, v136, s79, v161
	v_lshl_add_u32 v177, v135, 2, s80
	s_lshl_b32 s2, s43, s13
	s_lshl_b32 s2, s2, 7
	s_add_u32 s86, s20, s2
	s_addc_u32 s87, s21, 0
	s_add_i32 s2, s42, -64
	v_add_u32_e32 v136, s2, v164
	v_ashrrev_i32_e32 v136, 2, v136
	v_med3_i32 v136, v136, 0, s14
	v_lshl_add_u32 v136, v136, 9, v178
	global_load_dwordx4 v[0:3], v136, s[86:87]
	s_add_i32 s2, s42, -56
	v_add_u32_e32 v135, s2, v164
	v_ashrrev_i32_e32 v135, 2, v135
	v_med3_i32 v135, v135, 0, s14
	v_lshl_add_u32 v135, v135, 9, v178
	global_load_dwordx4 v[4:7], v135, s[86:87]
	s_add_i32 s2, s42, -48
	v_add_u32_e32 v136, s2, v164
	v_ashrrev_i32_e32 v136, 2, v136
	v_med3_i32 v136, v136, 0, s14
	v_lshl_add_u32 v136, v136, 9, v178
	global_load_dwordx4 v[8:11], v136, s[86:87]
	s_add_i32 s2, s42, -40
	v_add_u32_e32 v135, s2, v164
	v_ashrrev_i32_e32 v135, 2, v135
	v_med3_i32 v135, v135, 0, s14
	v_lshl_add_u32 v135, v135, 9, v178
	global_load_dwordx4 v[12:15], v135, s[86:87]
	s_add_i32 s2, s42, -32
	v_add_u32_e32 v136, s2, v164
	v_ashrrev_i32_e32 v136, 2, v136
	v_med3_i32 v136, v136, 0, s14
	v_lshl_add_u32 v136, v136, 9, v178
	global_load_dwordx4 v[16:19], v136, s[86:87]
	s_add_i32 s2, s42, -24
	v_add_u32_e32 v135, s2, v164
	v_ashrrev_i32_e32 v135, 2, v135
	v_med3_i32 v135, v135, 0, s14
	v_lshl_add_u32 v135, v135, 9, v178
	global_load_dwordx4 v[20:23], v135, s[86:87]
	s_add_i32 s2, s42, -16
	v_add_u32_e32 v136, s2, v164
	v_ashrrev_i32_e32 v136, 2, v136
	v_med3_i32 v136, v136, 0, s14
	v_lshl_add_u32 v136, v136, 9, v178
	global_load_dwordx4 v[24:27], v136, s[86:87]
	s_add_i32 s2, s42, -8
	v_add_u32_e32 v135, s2, v164
	v_ashrrev_i32_e32 v135, 2, v135
	v_med3_i32 v135, v135, 0, s14
	v_lshl_add_u32 v135, v135, 9, v178
	global_load_dwordx4 v[28:31], v135, s[86:87]
	s_add_i32 s2, s42, 0
	v_add_u32_e32 v136, s2, v164
	v_ashrrev_i32_e32 v136, 2, v136
	v_med3_i32 v136, v136, 0, s14
	v_lshl_add_u32 v136, v136, 9, v178
	global_load_dwordx4 v[32:35], v136, s[86:87]
	s_add_i32 s2, s42, 8
	v_add_u32_e32 v135, s2, v164
	v_ashrrev_i32_e32 v135, 2, v135
	v_med3_i32 v135, v135, 0, s14
	v_lshl_add_u32 v135, v135, 9, v178
	global_load_dwordx4 v[36:39], v135, s[86:87]
	s_add_i32 s2, s42, 16
	v_add_u32_e32 v136, s2, v164
	v_ashrrev_i32_e32 v136, 2, v136
	v_med3_i32 v136, v136, 0, s14
	v_lshl_add_u32 v136, v136, 9, v178
	global_load_dwordx4 v[40:43], v136, s[86:87]
	s_add_i32 s2, s42, 24
	v_add_u32_e32 v135, s2, v164
	v_ashrrev_i32_e32 v135, 2, v135
	v_med3_i32 v135, v135, 0, s14
	v_lshl_add_u32 v135, v135, 9, v178
	global_load_dwordx4 v[44:47], v135, s[86:87]
	s_lshl_b32 s2, s43, s13
	s_lshl_b32 s2, s2, 7
	s_add_u32 s74, s22, s2
	s_addc_u32 s75, s23, 0
	s_add_i32 s2, s42, -64
	v_add_u32_e32 v137, s2, v164
	v_ashrrev_i32_e32 v137, 2, v137
	v_med3_i32 v137, v137, 0, s14
	v_lshl_add_u32 v137, v137, 9, v178
	global_load_dwordx4 v[64:67], v137, s[74:75]
	s_add_i32 s2, s42, -56
	v_add_u32_e32 v137, s2, v164
	v_ashrrev_i32_e32 v137, 2, v137
	v_med3_i32 v137, v137, 0, s14
	v_lshl_add_u32 v137, v137, 9, v178
	global_load_dwordx4 v[68:71], v137, s[74:75]
	s_add_i32 s2, s42, -48
	v_add_u32_e32 v137, s2, v164
	v_ashrrev_i32_e32 v137, 2, v137
	v_med3_i32 v137, v137, 0, s14
	v_lshl_add_u32 v137, v137, 9, v178
	global_load_dwordx4 v[72:75], v137, s[74:75]
	s_add_i32 s2, s42, -40
	v_add_u32_e32 v137, s2, v164
	v_ashrrev_i32_e32 v137, 2, v137
	v_med3_i32 v137, v137, 0, s14
	v_lshl_add_u32 v137, v137, 9, v178
	global_load_dwordx4 v[76:79], v137, s[74:75]
	s_lshl_b32 s2, s43, s13
	s_lshl_b32 s2, s2, 7
	s_add_u32 s74, s22, s2
	s_addc_u32 s75, s23, 0
	s_add_i32 s2, s42, -32
	v_add_u32_e32 v137, s2, v164
	v_ashrrev_i32_e32 v137, 2, v137
	v_med3_i32 v137, v137, 0, s14
	v_lshl_add_u32 v137, v137, 9, v178
	global_load_dwordx4 v[80:83], v137, s[74:75]
	s_add_i32 s2, s42, -24
	v_add_u32_e32 v137, s2, v164
	v_ashrrev_i32_e32 v137, 2, v137
	v_med3_i32 v137, v137, 0, s14
	v_lshl_add_u32 v137, v137, 9, v178
	global_load_dwordx4 v[84:87], v137, s[74:75]
	s_add_i32 s2, s42, -16
	v_add_u32_e32 v137, s2, v164
	v_ashrrev_i32_e32 v137, 2, v137
	v_med3_i32 v137, v137, 0, s14
	v_lshl_add_u32 v137, v137, 9, v178
	global_load_dwordx4 v[88:91], v137, s[74:75]
	s_add_i32 s2, s42, -8
	v_add_u32_e32 v137, s2, v164
	v_ashrrev_i32_e32 v137, 2, v137
	v_med3_i32 v137, v137, 0, s14
	v_lshl_add_u32 v137, v137, 9, v178
	global_load_dwordx4 v[92:95], v137, s[74:75]
	s_lshl_b32 s2, s43, s13
	s_lshl_b32 s2, s2, 7
	s_add_u32 s74, s22, s2
	s_addc_u32 s75, s23, 0
	s_add_i32 s2, s42, 0
	v_add_u32_e32 v137, s2, v164
	v_ashrrev_i32_e32 v137, 2, v137
	v_med3_i32 v137, v137, 0, s14
	v_lshl_add_u32 v137, v137, 9, v178
	global_load_dwordx4 v[96:99], v137, s[74:75]
	s_add_i32 s2, s42, 8
	v_add_u32_e32 v137, s2, v164
	v_ashrrev_i32_e32 v137, 2, v137
	v_med3_i32 v137, v137, 0, s14
	v_lshl_add_u32 v137, v137, 9, v178
	global_load_dwordx4 v[100:103], v137, s[74:75]
	s_add_i32 s2, s42, 16
	v_add_u32_e32 v137, s2, v164
	v_ashrrev_i32_e32 v137, 2, v137
	v_med3_i32 v137, v137, 0, s14
	v_lshl_add_u32 v137, v137, 9, v178
	global_load_dwordx4 v[104:107], v137, s[74:75]
	s_add_i32 s2, s42, 24
	v_add_u32_e32 v137, s2, v164
	v_ashrrev_i32_e32 v137, 2, v137
	v_med3_i32 v137, v137, 0, s14
	v_lshl_add_u32 v137, v137, 9, v178
	global_load_dwordx4 v[108:111], v137, s[74:75]
	v_subrev_u32_e32 v143, s80, v174
	v_lshl_add_u32 v143, v143, 5, v161
	v_add_u32_e32 v143, 0x1b500, v143
	ds_read_b128 v[48:51], v143
	ds_read_b128 v[52:55], v143 offset:64
	ds_read_b128 v[56:59], v143 offset:2048
	ds_read_b128 v[60:63], v143 offset:2112
	s_waitcnt lgkmcnt(0)
	v_mov_b32_e32 v138, 0
	v_mov_b32_e32 v139, 0
	v_mov_b32_e32 v140, 0
	v_mov_b32_e32 v141, 0
	ds_read_b128 v[204:207], v149
	ds_read_b128 v[208:211], v149 offset:64
	ds_read_b128 v[212:215], v149 offset:2304
	ds_read_b128 v[216:219], v149 offset:2368
	ds_read_b128 v[220:223], v149 offset:4608
	ds_read_b128 v[224:227], v149 offset:4672
	ds_read_b128 v[228:231], v149 offset:6912
	ds_read_b128 v[232:235], v149 offset:6976
	s_waitcnt lgkmcnt(0)
	v_mfma_f32_16x16x32_bf16 v[236:239], v[204:207], v[48:51], 0
	v_mfma_f32_16x16x32_bf16 v[236:239], v[208:211], v[52:55], v[236:239]
	v_mfma_f32_16x16x32_bf16 v[240:243], v[212:215], v[48:51], 0
	v_mfma_f32_16x16x32_bf16 v[240:243], v[216:219], v[52:55], v[240:243]
	v_mfma_f32_16x16x32_bf16 v[248:251], v[212:215], v[56:59], 0
	v_mfma_f32_16x16x32_bf16 v[248:251], v[216:219], v[60:63], v[248:251]
	s_nop 7
	s_add_i32 s77, s40, -64
	s_cmp_lt_u32 s77, s44
	s_cselect_b32 s76, s70, s71
	v_min_f32_e32 v152, s76, v236
	v_min_f32_e32 v153, s76, v237
	v_min_f32_e32 v154, s76, v238
	v_min_f32_e32 v155, s76, v239
	v_mfma_f32_16x16x32_bf16 v[236:239], v[220:223], v[48:51], 0
	v_mfma_f32_16x16x32_bf16 v[236:239], v[224:227], v[52:55], v[236:239]
	v_mfma_f32_16x16x32_bf16 v[244:247], v[220:223], v[56:59], 0
	v_mfma_f32_16x16x32_bf16 v[244:247], v[224:227], v[60:63], v[244:247]
	ds_read_b128 v[204:207], v149 offset:9216
	ds_read_b128 v[208:211], v149 offset:9280
	v_mul_f32_e32 v152, s72, v152
	v_mul_f32_e32 v153, s72, v153
	v_mul_f32_e32 v154, s72, v154
	v_mul_f32_e32 v155, s72, v155
	v_exp_f32_e32 v152, v152
	v_exp_f32_e32 v153, v153
	v_exp_f32_e32 v154, v154
	v_exp_f32_e32 v155, v155
	v_cndmask_b32_e64 v152, 0, v152, s[54:55]
	v_cndmask_b32_e64 v153, 0, v153, s[56:57]
	v_cndmask_b32_e64 v154, 0, v154, s[58:59]
	v_cndmask_b32_e64 v155, 0, v155, s[60:61]
	v_add_f32_e32 v138, v138, v152
	v_add_f32_e32 v139, v139, v153
	v_add_f32_e32 v138, v138, v154
	v_add_f32_e32 v139, v139, v155
	v_cvt_pk_bf16_f32 v112, v152, v153
	v_cvt_pk_bf16_f32 v113, v154, v155
	s_add_i32 s77, s40, -48
	s_cmp_lt_u32 s77, s44
	s_cselect_b32 s76, s70, s71
	v_min_f32_e32 v152, s76, v240
	v_min_f32_e32 v153, s76, v241
	v_min_f32_e32 v154, s76, v242
	v_min_f32_e32 v155, s76, v243
	v_min_f32_e32 v156, s76, v248
	v_min_f32_e32 v157, s76, v249
	v_min_f32_e32 v158, s76, v250
	v_min_f32_e32 v159, s76, v251
	v_mfma_f32_16x16x32_bf16 v[240:243], v[228:231], v[48:51], 0
	v_mfma_f32_16x16x32_bf16 v[240:243], v[232:235], v[52:55], v[240:243]
	v_mfma_f32_16x16x32_bf16 v[248:251], v[228:231], v[56:59], 0
	v_mfma_f32_16x16x32_bf16 v[248:251], v[232:235], v[60:63], v[248:251]
	ds_read_b128 v[212:215], v149 offset:11520
	ds_read_b128 v[216:219], v149 offset:11584
	v_mul_f32_e32 v152, s72, v152
	v_mul_f32_e32 v153, s72, v153
	v_mul_f32_e32 v154, s72, v154
	v_mul_f32_e32 v155, s72, v155
	v_exp_f32_e32 v152, v152
	v_exp_f32_e32 v153, v153
	v_exp_f32_e32 v154, v154
	v_exp_f32_e32 v155, v155
	v_add_f32_e32 v138, v138, v152
	v_add_f32_e32 v139, v139, v153
	v_add_f32_e32 v138, v138, v154
	v_add_f32_e32 v139, v139, v155
	v_cvt_pk_bf16_f32 v114, v152, v153
	v_cvt_pk_bf16_f32 v115, v154, v155
	v_mul_f32_e32 v156, s72, v156
	v_mul_f32_e32 v157, s72, v157
	v_mul_f32_e32 v158, s72, v158
	v_mul_f32_e32 v159, s72, v159
	v_exp_f32_e32 v156, v156
	v_exp_f32_e32 v157, v157
	v_exp_f32_e32 v158, v158
	v_exp_f32_e32 v159, v159
	v_cndmask_b32_e64 v156, 0, v156, s[54:55]
	v_cndmask_b32_e64 v157, 0, v157, s[56:57]
	v_cndmask_b32_e64 v158, 0, v158, s[58:59]
	v_cndmask_b32_e64 v159, 0, v159, s[60:61]
	v_add_f32_e32 v140, v140, v156
	v_add_f32_e32 v141, v141, v157
	v_add_f32_e32 v140, v140, v158
	v_add_f32_e32 v141, v141, v159
	v_cvt_pk_bf16_f32 v186, v156, v157
	v_cvt_pk_bf16_f32 v187, v158, v159
	s_add_i32 s77, s40, -32
	s_cmp_lt_u32 s77, s44
	s_cselect_b32 s76, s70, s71
	v_min_f32_e32 v152, s76, v236
	v_min_f32_e32 v153, s76, v237
	v_min_f32_e32 v154, s76, v238
	v_min_f32_e32 v155, s76, v239
	v_min_f32_e32 v156, s76, v244
	v_min_f32_e32 v157, s76, v245
	v_min_f32_e32 v158, s76, v246
	v_min_f32_e32 v159, s76, v247
	s_waitcnt lgkmcnt(2)
	v_mfma_f32_16x16x32_bf16 v[236:239], v[204:207], v[48:51], 0
	v_mfma_f32_16x16x32_bf16 v[236:239], v[208:211], v[52:55], v[236:239]
	v_mfma_f32_16x16x32_bf16 v[244:247], v[204:207], v[56:59], 0
	v_mfma_f32_16x16x32_bf16 v[244:247], v[208:211], v[60:63], v[244:247]
	ds_read_b128 v[220:223], v149 offset:13824
	ds_read_b128 v[224:227], v149 offset:13888
	v_mul_f32_e32 v152, s72, v152
	v_mul_f32_e32 v153, s72, v153
	v_mul_f32_e32 v154, s72, v154
	v_mul_f32_e32 v155, s72, v155
	v_exp_f32_e32 v152, v152
	v_exp_f32_e32 v153, v153
	v_exp_f32_e32 v154, v154
	v_exp_f32_e32 v155, v155
	v_add_f32_e32 v138, v138, v152
	v_add_f32_e32 v139, v139, v153
	v_add_f32_e32 v138, v138, v154
	v_add_f32_e32 v139, v139, v155
	v_cvt_pk_bf16_f32 v116, v152, v153
	v_cvt_pk_bf16_f32 v117, v154, v155
	v_mul_f32_e32 v156, s72, v156
	v_mul_f32_e32 v157, s72, v157
	v_mul_f32_e32 v158, s72, v158
	v_mul_f32_e32 v159, s72, v159
	v_exp_f32_e32 v156, v156
	v_exp_f32_e32 v157, v157
	v_exp_f32_e32 v158, v158
	v_exp_f32_e32 v159, v159
	v_add_f32_e32 v140, v140, v156
	v_add_f32_e32 v141, v141, v157
	v_add_f32_e32 v140, v140, v158
	v_add_f32_e32 v141, v141, v159
	v_cvt_pk_bf16_f32 v188, v156, v157
	v_cvt_pk_bf16_f32 v189, v158, v159
	s_add_i32 s77, s40, -16
	s_cmp_lt_u32 s77, s44
	s_cselect_b32 s76, s70, s71
	v_min_f32_e32 v152, s76, v240
	v_min_f32_e32 v153, s76, v241
	v_min_f32_e32 v154, s76, v242
	v_min_f32_e32 v155, s76, v243
	v_min_f32_e32 v156, s76, v248
	v_min_f32_e32 v157, s76, v249
	v_min_f32_e32 v158, s76, v250
	v_min_f32_e32 v159, s76, v251
	s_waitcnt lgkmcnt(2)
	v_mfma_f32_16x16x32_bf16 v[240:243], v[212:215], v[48:51], 0
	v_mfma_f32_16x16x32_bf16 v[240:243], v[216:219], v[52:55], v[240:243]
	v_mfma_f32_16x16x32_bf16 v[248:251], v[212:215], v[56:59], 0
	v_mfma_f32_16x16x32_bf16 v[248:251], v[216:219], v[60:63], v[248:251]
	ds_read_b128 v[228:231], v149 offset:16128
	ds_read_b128 v[232:235], v149 offset:16192
	v_mul_f32_e32 v152, s72, v152
	v_mul_f32_e32 v153, s72, v153
	v_mul_f32_e32 v154, s72, v154
	v_mul_f32_e32 v155, s72, v155
	v_exp_f32_e32 v152, v152
	v_exp_f32_e32 v153, v153
	v_exp_f32_e32 v154, v154
	v_exp_f32_e32 v155, v155
	v_add_f32_e32 v138, v138, v152
	v_add_f32_e32 v139, v139, v153
	v_add_f32_e32 v138, v138, v154
	v_add_f32_e32 v139, v139, v155
	v_cvt_pk_bf16_f32 v118, v152, v153
	v_cvt_pk_bf16_f32 v119, v154, v155
	v_mul_f32_e32 v156, s72, v156
	v_mul_f32_e32 v157, s72, v157
	v_mul_f32_e32 v158, s72, v158
	v_mul_f32_e32 v159, s72, v159
	v_exp_f32_e32 v156, v156
	v_exp_f32_e32 v157, v157
	v_exp_f32_e32 v158, v158
	v_exp_f32_e32 v159, v159
	v_add_f32_e32 v140, v140, v156
	v_add_f32_e32 v141, v141, v157
	v_add_f32_e32 v140, v140, v158
	v_add_f32_e32 v141, v141, v159
	v_cvt_pk_bf16_f32 v190, v156, v157
	v_cvt_pk_bf16_f32 v191, v158, v159
	s_add_i32 s77, s40, 0
	s_cmp_lt_u32 s77, s44
	s_cselect_b32 s76, s70, s71
	v_min_f32_e32 v152, s76, v236
	v_min_f32_e32 v153, s76, v237
	v_min_f32_e32 v154, s76, v238
	v_min_f32_e32 v155, s76, v239
	v_min_f32_e32 v156, s76, v244
	v_min_f32_e32 v157, s76, v245
	v_min_f32_e32 v158, s76, v246
	v_min_f32_e32 v159, s76, v247
	s_waitcnt lgkmcnt(2)
	v_mfma_f32_16x16x32_bf16 v[236:239], v[220:223], v[48:51], 0
	v_mfma_f32_16x16x32_bf16 v[236:239], v[224:227], v[52:55], v[236:239]
	v_mfma_f32_16x16x32_bf16 v[244:247], v[220:223], v[56:59], 0
	v_mfma_f32_16x16x32_bf16 v[244:247], v[224:227], v[60:63], v[244:247]
	ds_read_b128 v[204:207], v149 offset:18432
	ds_read_b128 v[208:211], v149 offset:18496
	v_mul_f32_e32 v152, s72, v152
	v_mul_f32_e32 v153, s72, v153
	v_mul_f32_e32 v154, s72, v154
	v_mul_f32_e32 v155, s72, v155
	v_exp_f32_e32 v152, v152
	v_exp_f32_e32 v153, v153
	v_exp_f32_e32 v154, v154
	v_exp_f32_e32 v155, v155
	v_add_f32_e32 v138, v138, v152
	v_add_f32_e32 v139, v139, v153
	v_add_f32_e32 v138, v138, v154
	v_add_f32_e32 v139, v139, v155
	v_cvt_pk_bf16_f32 v120, v152, v153
	v_cvt_pk_bf16_f32 v121, v154, v155
	v_mul_f32_e32 v156, s72, v156
	v_mul_f32_e32 v157, s72, v157
	v_mul_f32_e32 v158, s72, v158
	v_mul_f32_e32 v159, s72, v159
	v_exp_f32_e32 v156, v156
	v_exp_f32_e32 v157, v157
	v_exp_f32_e32 v158, v158
	v_exp_f32_e32 v159, v159
	v_add_f32_e32 v140, v140, v156
	v_add_f32_e32 v141, v141, v157
	v_add_f32_e32 v140, v140, v158
	v_add_f32_e32 v141, v141, v159
	v_cvt_pk_bf16_f32 v192, v156, v157
	v_cvt_pk_bf16_f32 v193, v158, v159
	s_add_i32 s77, s40, 16
	s_cmp_lt_u32 s77, s44
	s_cselect_b32 s76, s70, s71
	v_min_f32_e32 v152, s76, v240
	v_min_f32_e32 v153, s76, v241
	v_min_f32_e32 v154, s76, v242
	v_min_f32_e32 v155, s76, v243
	v_min_f32_e32 v156, s76, v248
	v_min_f32_e32 v157, s76, v249
	v_min_f32_e32 v158, s76, v250
	v_min_f32_e32 v159, s76, v251
	s_waitcnt lgkmcnt(2)
	v_mfma_f32_16x16x32_bf16 v[240:243], v[228:231], v[48:51], 0
	v_mfma_f32_16x16x32_bf16 v[240:243], v[232:235], v[52:55], v[240:243]
	v_mfma_f32_16x16x32_bf16 v[248:251], v[228:231], v[56:59], 0
	v_mfma_f32_16x16x32_bf16 v[248:251], v[232:235], v[60:63], v[248:251]
	ds_read_b128 v[212:215], v149 offset:20736
	ds_read_b128 v[216:219], v149 offset:20800
	v_mul_f32_e32 v152, s72, v152
	v_mul_f32_e32 v153, s72, v153
	v_mul_f32_e32 v154, s72, v154
	v_mul_f32_e32 v155, s72, v155
	v_exp_f32_e32 v152, v152
	v_exp_f32_e32 v153, v153
	v_exp_f32_e32 v154, v154
	v_exp_f32_e32 v155, v155
	v_add_f32_e32 v138, v138, v152
	v_add_f32_e32 v139, v139, v153
	v_add_f32_e32 v138, v138, v154
	v_add_f32_e32 v139, v139, v155
	v_cvt_pk_bf16_f32 v122, v152, v153
	v_cvt_pk_bf16_f32 v123, v154, v155
	v_mul_f32_e32 v156, s72, v156
	v_mul_f32_e32 v157, s72, v157
	v_mul_f32_e32 v158, s72, v158
	v_mul_f32_e32 v159, s72, v159
	v_exp_f32_e32 v156, v156
	v_exp_f32_e32 v157, v157
	v_exp_f32_e32 v158, v158
	v_exp_f32_e32 v159, v159
	v_add_f32_e32 v140, v140, v156
	v_add_f32_e32 v141, v141, v157
	v_add_f32_e32 v140, v140, v158
	v_add_f32_e32 v141, v141, v159
	v_cvt_pk_bf16_f32 v194, v156, v157
	v_cvt_pk_bf16_f32 v195, v158, v159
	s_add_i32 s77, s40, 32
	s_cmp_lt_u32 s77, s44
	s_cselect_b32 s76, s70, s71
	v_min_f32_e32 v152, s76, v236
	v_min_f32_e32 v153, s76, v237
	v_min_f32_e32 v154, s76, v238
	v_min_f32_e32 v155, s76, v239
	v_min_f32_e32 v156, s76, v244
	v_min_f32_e32 v157, s76, v245
	v_min_f32_e32 v158, s76, v246
	v_min_f32_e32 v159, s76, v247
	s_waitcnt lgkmcnt(2)
	v_mfma_f32_16x16x32_bf16 v[236:239], v[204:207], v[48:51], 0
	v_mfma_f32_16x16x32_bf16 v[236:239], v[208:211], v[52:55], v[236:239]
	v_mfma_f32_16x16x32_bf16 v[244:247], v[204:207], v[56:59], 0
	v_mfma_f32_16x16x32_bf16 v[244:247], v[208:211], v[60:63], v[244:247]
	v_mul_f32_e32 v152, s72, v152
	v_mul_f32_e32 v153, s72, v153
	v_mul_f32_e32 v154, s72, v154
	v_mul_f32_e32 v155, s72, v155
	v_exp_f32_e32 v152, v152
	v_exp_f32_e32 v153, v153
	v_exp_f32_e32 v154, v154
	v_exp_f32_e32 v155, v155
	v_add_f32_e32 v138, v138, v152
	v_add_f32_e32 v139, v139, v153
	v_add_f32_e32 v138, v138, v154
	v_add_f32_e32 v139, v139, v155
	v_cvt_pk_bf16_f32 v124, v152, v153
	v_cvt_pk_bf16_f32 v125, v154, v155
	v_mul_f32_e32 v156, s72, v156
	v_mul_f32_e32 v157, s72, v157
	v_mul_f32_e32 v158, s72, v158
	v_mul_f32_e32 v159, s72, v159
	v_exp_f32_e32 v156, v156
	v_exp_f32_e32 v157, v157
	v_exp_f32_e32 v158, v158
	v_exp_f32_e32 v159, v159
	v_add_f32_e32 v140, v140, v156
	v_add_f32_e32 v141, v141, v157
	v_add_f32_e32 v140, v140, v158
	v_add_f32_e32 v141, v141, v159
	v_cvt_pk_bf16_f32 v196, v156, v157
	v_cvt_pk_bf16_f32 v197, v158, v159
	s_add_i32 s77, s40, 48
	s_cmp_lt_u32 s77, s44
	s_cselect_b32 s76, s70, s71
	v_min_f32_e32 v152, s76, v240
	v_min_f32_e32 v153, s76, v241
	v_min_f32_e32 v154, s76, v242
	v_min_f32_e32 v155, s76, v243
	v_min_f32_e32 v156, s76, v248
	v_min_f32_e32 v157, s76, v249
	v_min_f32_e32 v158, s76, v250
	v_min_f32_e32 v159, s76, v251
	s_waitcnt lgkmcnt(0)
	v_mfma_f32_16x16x32_bf16 v[248:251], v[212:215], v[56:59], 0
	v_mfma_f32_16x16x32_bf16 v[248:251], v[216:219], v[60:63], v[248:251]
	v_mul_f32_e32 v152, s72, v152
	v_mul_f32_e32 v153, s72, v153
	v_mul_f32_e32 v154, s72, v154
	v_mul_f32_e32 v155, s72, v155
	v_exp_f32_e32 v152, v152
	v_exp_f32_e32 v153, v153
	v_exp_f32_e32 v154, v154
	v_exp_f32_e32 v155, v155
	v_add_f32_e32 v138, v138, v152
	v_add_f32_e32 v139, v139, v153
	v_add_f32_e32 v138, v138, v154
	v_add_f32_e32 v139, v139, v155
	v_cvt_pk_bf16_f32 v126, v152, v153
	v_cvt_pk_bf16_f32 v127, v154, v155
	v_mul_f32_e32 v156, s72, v156
	v_mul_f32_e32 v157, s72, v157
	v_mul_f32_e32 v158, s72, v158
	v_mul_f32_e32 v159, s72, v159
	v_exp_f32_e32 v156, v156
	v_exp_f32_e32 v157, v157
	v_exp_f32_e32 v158, v158
	v_exp_f32_e32 v159, v159
	v_add_f32_e32 v140, v140, v156
	v_add_f32_e32 v141, v141, v157
	v_add_f32_e32 v140, v140, v158
	v_add_f32_e32 v141, v141, v159
	v_cvt_pk_bf16_f32 v198, v156, v157
	v_cvt_pk_bf16_f32 v199, v158, v159
	s_add_i32 s77, s40, 64
	s_cmp_lt_u32 s77, s44
	s_cselect_b32 s76, s70, s71
	v_min_f32_e32 v152, s76, v236
	v_min_f32_e32 v153, s76, v237
	v_min_f32_e32 v154, s76, v238
	v_min_f32_e32 v155, s76, v239
	v_min_f32_e32 v156, s76, v244
	v_min_f32_e32 v157, s76, v245
	v_min_f32_e32 v158, s76, v246
	v_min_f32_e32 v159, s76, v247
	v_mul_f32_e32 v152, s72, v152
	v_mul_f32_e32 v153, s72, v153
	v_mul_f32_e32 v154, s72, v154
	v_mul_f32_e32 v155, s72, v155
	v_exp_f32_e32 v152, v152
	v_exp_f32_e32 v153, v153
	v_exp_f32_e32 v154, v154
	v_exp_f32_e32 v155, v155
	v_cndmask_b32_e64 v152, 0, v152, s[62:63]
	v_cndmask_b32_e64 v153, 0, v153, s[64:65]
	v_cndmask_b32_e64 v154, 0, v154, s[66:67]
	v_cndmask_b32_e64 v155, 0, v155, s[68:69]
	v_add_f32_e32 v138, v138, v152
	v_add_f32_e32 v139, v139, v153
	v_add_f32_e32 v138, v138, v154
	v_add_f32_e32 v139, v139, v155
	v_cvt_pk_bf16_f32 v128, v152, v153
	v_cvt_pk_bf16_f32 v129, v154, v155
	v_mul_f32_e32 v156, s72, v156
	v_mul_f32_e32 v157, s72, v157
	v_mul_f32_e32 v158, s72, v158
	v_mul_f32_e32 v159, s72, v159
	v_exp_f32_e32 v156, v156
	v_exp_f32_e32 v157, v157
	v_exp_f32_e32 v158, v158
	v_exp_f32_e32 v159, v159
	v_add_f32_e32 v140, v140, v156
	v_add_f32_e32 v141, v141, v157
	v_add_f32_e32 v140, v140, v158
	v_add_f32_e32 v141, v141, v159
	v_cvt_pk_bf16_f32 v200, v156, v157
	v_cvt_pk_bf16_f32 v201, v158, v159
	s_add_i32 s77, s40, 80
	s_cmp_lt_u32 s77, s44
	s_cselect_b32 s76, s70, s71
	v_min_f32_e32 v156, s76, v248
	v_min_f32_e32 v157, s76, v249
	v_min_f32_e32 v158, s76, v250
	v_min_f32_e32 v159, s76, v251
	v_mul_f32_e32 v156, s72, v156
	v_mul_f32_e32 v157, s72, v157
	v_mul_f32_e32 v158, s72, v158
	v_mul_f32_e32 v159, s72, v159
	v_exp_f32_e32 v156, v156
	v_exp_f32_e32 v157, v157
	v_exp_f32_e32 v158, v158
	v_exp_f32_e32 v159, v159
	v_cndmask_b32_e64 v156, 0, v156, s[62:63]
	v_cndmask_b32_e64 v157, 0, v157, s[64:65]
	v_cndmask_b32_e64 v158, 0, v158, s[66:67]
	v_cndmask_b32_e64 v159, 0, v159, s[68:69]
	v_add_f32_e32 v140, v140, v156
	v_add_f32_e32 v141, v141, v157
	v_add_f32_e32 v140, v140, v158
	v_add_f32_e32 v141, v141, v159
	v_cvt_pk_bf16_f32 v202, v156, v157
	v_cvt_pk_bf16_f32 v203, v158, v159
	v_add_f32_e32 v132, v138, v139
	v_add_f32_e32 v133, v140, v141
	ds_bpermute_b32 v142, v167, v132
	ds_bpermute_b32 v143, v167, v133
	ds_read_b64_tr_b16 v[236:237], v151 offset:0
	ds_read_b64_tr_b16 v[238:239], v151 offset:2304
	ds_read_b64_tr_b16 v[240:241], v151 offset:32
	ds_read_b64_tr_b16 v[242:243], v151 offset:2336
	ds_read_b64_tr_b16 v[244:245], v151 offset:64
	ds_read_b64_tr_b16 v[246:247], v151 offset:2368
	ds_read_b64_tr_b16 v[248:249], v151 offset:96
	ds_read_b64_tr_b16 v[250:251], v151 offset:2400
	s_waitcnt lgkmcnt(0)
	v_add_f32_e32 v132, v132, v142
	v_add_f32_e32 v133, v133, v143
	ds_bpermute_b32 v142, v168, v132
	ds_bpermute_b32 v143, v168, v133
	ds_read_b64_tr_b16 v[48:49], v151 offset:4608
	ds_read_b64_tr_b16 v[50:51], v151 offset:6912
	ds_read_b64_tr_b16 v[52:53], v151 offset:4640
	ds_read_b64_tr_b16 v[54:55], v151 offset:6944
	ds_read_b64_tr_b16 v[56:57], v151 offset:4672
	ds_read_b64_tr_b16 v[58:59], v151 offset:6976
	ds_read_b64_tr_b16 v[60:61], v151 offset:4704
	ds_read_b64_tr_b16 v[62:63], v151 offset:7008
	v_mfma_f32_16x16x32_bf16 v[204:207], v[236:239], v[112:115], 0
	v_mfma_f32_16x16x32_bf16 v[208:211], v[240:243], v[112:115], 0
	v_mfma_f32_16x16x32_bf16 v[212:215], v[244:247], v[112:115], 0
	v_mfma_f32_16x16x32_bf16 v[216:219], v[248:251], v[112:115], 0
	v_mfma_f32_16x16x32_bf16 v[220:223], v[236:239], v[184:187], 0
	v_mfma_f32_16x16x32_bf16 v[224:227], v[240:243], v[184:187], 0
	v_mfma_f32_16x16x32_bf16 v[228:231], v[244:247], v[184:187], 0
	v_mfma_f32_16x16x32_bf16 v[232:235], v[248:251], v[184:187], 0
	s_waitcnt lgkmcnt(0)
	v_add_f32_e32 v132, v132, v142
	v_add_f32_e32 v133, v133, v143
	ds_read_b64_tr_b16 v[236:237], v151 offset:9216
	ds_read_b64_tr_b16 v[238:239], v151 offset:11520
	ds_read_b64_tr_b16 v[240:241], v151 offset:9248
	ds_read_b64_tr_b16 v[242:243], v151 offset:11552
	ds_read_b64_tr_b16 v[244:245], v151 offset:9280
	ds_read_b64_tr_b16 v[246:247], v151 offset:11584
	ds_read_b64_tr_b16 v[248:249], v151 offset:9312
	ds_read_b64_tr_b16 v[250:251], v151 offset:11616
	v_mfma_f32_16x16x32_bf16 v[204:207], v[48:51], v[116:119], v[204:207]
	v_mfma_f32_16x16x32_bf16 v[208:211], v[52:55], v[116:119], v[208:211]
	v_mfma_f32_16x16x32_bf16 v[212:215], v[56:59], v[116:119], v[212:215]
	v_mfma_f32_16x16x32_bf16 v[216:219], v[60:63], v[116:119], v[216:219]
	v_mfma_f32_16x16x32_bf16 v[220:223], v[48:51], v[188:191], v[220:223]
	v_mfma_f32_16x16x32_bf16 v[224:227], v[52:55], v[188:191], v[224:227]
	v_mfma_f32_16x16x32_bf16 v[228:231], v[56:59], v[188:191], v[228:231]
	v_mfma_f32_16x16x32_bf16 v[232:235], v[60:63], v[188:191], v[232:235]
	s_waitcnt lgkmcnt(0)
	ds_read_b64_tr_b16 v[48:49], v151 offset:13824
	ds_read_b64_tr_b16 v[50:51], v151 offset:16128
	ds_read_b64_tr_b16 v[52:53], v151 offset:13856
	ds_read_b64_tr_b16 v[54:55], v151 offset:16160
	ds_read_b64_tr_b16 v[56:57], v151 offset:13888
	ds_read_b64_tr_b16 v[58:59], v151 offset:16192
	ds_read_b64_tr_b16 v[60:61], v151 offset:13920
	ds_read_b64_tr_b16 v[62:63], v151 offset:16224
	v_mfma_f32_16x16x32_bf16 v[204:207], v[236:239], v[120:123], v[204:207]
	v_mfma_f32_16x16x32_bf16 v[208:211], v[240:243], v[120:123], v[208:211]
	v_mfma_f32_16x16x32_bf16 v[212:215], v[244:247], v[120:123], v[212:215]
	v_mfma_f32_16x16x32_bf16 v[216:219], v[248:251], v[120:123], v[216:219]
	v_mfma_f32_16x16x32_bf16 v[220:223], v[236:239], v[192:195], v[220:223]
	v_mfma_f32_16x16x32_bf16 v[224:227], v[240:243], v[192:195], v[224:227]
	v_mfma_f32_16x16x32_bf16 v[228:231], v[244:247], v[192:195], v[228:231]
	v_mfma_f32_16x16x32_bf16 v[232:235], v[248:251], v[192:195], v[232:235]
	s_waitcnt lgkmcnt(0)
	ds_read_b64_tr_b16 v[236:237], v151 offset:18432
	ds_read_b64_tr_b16 v[238:239], v151 offset:20736
	ds_read_b64_tr_b16 v[240:241], v151 offset:18464
	ds_read_b64_tr_b16 v[242:243], v151 offset:20768
	ds_read_b64_tr_b16 v[244:245], v151 offset:18496
	ds_read_b64_tr_b16 v[246:247], v151 offset:20800
	ds_read_b64_tr_b16 v[248:249], v151 offset:18528
	ds_read_b64_tr_b16 v[250:251], v151 offset:20832
	v_mfma_f32_16x16x32_bf16 v[204:207], v[48:51], v[124:127], v[204:207]
	v_mfma_f32_16x16x32_bf16 v[208:211], v[52:55], v[124:127], v[208:211]
	v_mfma_f32_16x16x32_bf16 v[212:215], v[56:59], v[124:127], v[212:215]
	v_mfma_f32_16x16x32_bf16 v[216:219], v[60:63], v[124:127], v[216:219]
	v_mfma_f32_16x16x32_bf16 v[220:223], v[48:51], v[196:199], v[220:223]
	v_mfma_f32_16x16x32_bf16 v[224:227], v[52:55], v[196:199], v[224:227]
	v_mfma_f32_16x16x32_bf16 v[228:231], v[56:59], v[196:199], v[228:231]
	v_mfma_f32_16x16x32_bf16 v[232:235], v[60:63], v[196:199], v[232:235]
	s_waitcnt lgkmcnt(0)
	v_mfma_f32_16x16x32_bf16 v[204:207], v[236:239], v[128:131], v[204:207]
	v_mfma_f32_16x16x32_bf16 v[208:211], v[240:243], v[128:131], v[208:211]
	v_mfma_f32_16x16x32_bf16 v[212:215], v[244:247], v[128:131], v[212:215]
	v_mfma_f32_16x16x32_bf16 v[216:219], v[248:251], v[128:131], v[216:219]
	v_mfma_f32_16x16x32_bf16 v[220:223], v[236:239], v[200:203], v[220:223]
	v_mfma_f32_16x16x32_bf16 v[224:227], v[240:243], v[200:203], v[224:227]
	v_mfma_f32_16x16x32_bf16 v[228:231], v[244:247], v[200:203], v[228:231]
	v_mfma_f32_16x16x32_bf16 v[232:235], v[248:251], v[200:203], v[232:235]
	s_barrier
	s_add_i32 s2, s42, 32
	v_add_u32_e32 v136, s2, v164
	v_ashrrev_i32_e32 v136, 2, v136
	v_med3_i32 v136, v136, 0, s14
	v_lshl_add_u32 v136, v136, 9, v178
	global_load_dwordx4 v[120:123], v136, s[86:87]
	s_add_i32 s2, s42, 40
	v_add_u32_e32 v135, s2, v164
	v_ashrrev_i32_e32 v135, 2, v135
	v_med3_i32 v135, v135, 0, s14
	v_lshl_add_u32 v135, v135, 9, v178
	global_load_dwordx4 v[124:127], v135, s[86:87]
	s_add_i32 s2, s42, 48
	v_add_u32_e32 v136, s2, v164
	v_ashrrev_i32_e32 v136, 2, v136
	v_med3_i32 v136, v136, 0, s14
	v_lshl_add_u32 v136, v136, 9, v178
	global_load_dwordx4 v[192:195], v136, s[86:87]
	s_add_i32 s2, s42, 56
	v_add_u32_e32 v135, s2, v164
	v_ashrrev_i32_e32 v135, 2, v135
	v_med3_i32 v135, v135, 0, s14
	v_lshl_add_u32 v135, v135, 9, v178
	global_load_dwordx4 v[196:199], v135, s[86:87]
	ds_write_b128 v173, v[204:207] offset:0
	ds_write_b128 v173, v[208:211] offset:64
	ds_write_b128 v173, v[212:215] offset:128
	ds_write_b128 v173, v[216:219] offset:192
	ds_write_b32 v174, v132 offset:0
	ds_write_b128 v173, v[220:223] offset:4624
	ds_write_b128 v173, v[224:227] offset:4688
	ds_write_b128 v173, v[228:231] offset:4752
	ds_write_b128 v173, v[232:235] offset:4816
	ds_write_b32 v174, v133 offset:64
	s_mov_b32 s40, s42
	s_mov_b32 s41, s43
	v_mov_b32_e32 v173, v176
	v_mov_b32_e32 v174, v177
	s_lshr_b32 s44, s33, 2
	s_lshr_b32 s42, s15, 4
	s_add_i32 s43, s0, 0
	v_subrev_u32_e32 v143, s80, v174
	v_lshl_add_u32 v143, v143, 5, v161
	v_add_u32_e32 v143, 0x1b500, v143
	ds_read_b128 v[48:51], v143
	ds_read_b128 v[52:55], v143 offset:64
	ds_read_b128 v[56:59], v143 offset:8192
	ds_read_b128 v[60:63], v143 offset:8256
	s_waitcnt lgkmcnt(0)
	v_mov_b32_e32 v138, 0
	v_mov_b32_e32 v139, 0
	v_mov_b32_e32 v140, 0
	v_mov_b32_e32 v141, 0
	s_waitcnt vmcnt(24)
	ds_write_b128 v165, v[0:3]
	ds_write_b128 v165, v[4:7] offset:1152
	ds_write_b128 v165, v[8:11] offset:2304
	ds_write_b128 v165, v[12:15] offset:3456
	s_waitcnt lgkmcnt(0)
	ds_read_b128 v[204:207], v175
	ds_read_b128 v[208:211], v175 offset:64
	ds_read_b128 v[212:215], v175 offset:2304
	ds_read_b128 v[216:219], v175 offset:2368
	s_lshl_b32 s2, s41, s39
	s_lshl_b32 s2, s2, 7
	s_add_u32 s86, s24, s2
	s_addc_u32 s87, s25, 0
	s_add_i32 s2, s40, 64
	v_add_u32_e32 v136, s2, v164
	v_ashrrev_i32_e32 v136, 2, v136
	v_med3_i32 v136, v136, 0, s38
	v_lshl_add_u32 v136, v136, 9, v178
	global_load_dwordx4 v[0:3], v136, s[86:87]
	s_add_i32 s2, s40, 72
	v_add_u32_e32 v135, s2, v164
	v_ashrrev_i32_e32 v135, 2, v135
	v_med3_i32 v135, v135, 0, s38
	v_lshl_add_u32 v135, v135, 9, v178
	global_load_dwordx4 v[4:7], v135, s[86:87]
	s_add_i32 s2, s40, 80
	v_add_u32_e32 v136, s2, v164
	v_ashrrev_i32_e32 v136, 2, v136
	v_med3_i32 v136, v136, 0, s38
	v_lshl_add_u32 v136, v136, 9, v178
	global_load_dwordx4 v[8:11], v136, s[86:87]
	s_add_i32 s2, s40, 88
	v_add_u32_e32 v135, s2, v164
	v_ashrrev_i32_e32 v135, 2, v135
	v_med3_i32 v135, v135, 0, s38
	v_lshl_add_u32 v135, v135, 9, v178
	global_load_dwordx4 v[12:15], v135, s[86:87]
	s_waitcnt vmcnt(24)
	s_waitcnt lgkmcnt(0)
	ds_write_b128 v165, v[16:19]
	ds_write_b128 v165, v[20:23] offset:1152
	ds_write_b128 v165, v[24:27] offset:2304
	ds_write_b128 v165, v[28:31] offset:3456
	v_mfma_f32_16x16x32_bf16 v[236:239], v[204:207], v[48:51], 0
	v_mfma_f32_16x16x32_bf16 v[236:239], v[208:211], v[52:55], v[236:239]
	v_mfma_f32_16x16x32_bf16 v[240:243], v[212:215], v[48:51], 0
	v_mfma_f32_16x16x32_bf16 v[240:243], v[216:219], v[52:55], v[240:243]
	v_mfma_f32_16x16x32_bf16 v[248:251], v[212:215], v[56:59], 0
	v_mfma_f32_16x16x32_bf16 v[248:251], v[216:219], v[60:63], v[248:251]
	s_waitcnt lgkmcnt(0)
	ds_read_b128 v[220:223], v175
	ds_read_b128 v[224:227], v175 offset:64
	s_lshl_b32 s2, s41, s39
	s_lshl_b32 s2, s2, 7
	s_add_u32 s74, s26, s2
	s_addc_u32 s75, s27, 0
	s_add_i32 s2, s40, 32
	v_add_u32_e32 v137, s2, v164
	v_ashrrev_i32_e32 v137, 2, v137
	v_med3_i32 v137, v137, 0, s38
	v_lshl_add_u32 v137, v137, 9, v178
	global_load_dwordx4 v[16:19], v137, s[74:75]
	s_add_i32 s2, s40, 40
	v_add_u32_e32 v137, s2, v164
	v_ashrrev_i32_e32 v137, 2, v137
	v_med3_i32 v137, v137, 0, s38
	v_lshl_add_u32 v137, v137, 9, v178
	global_load_dwordx4 v[20:23], v137, s[74:75]
	s_add_i32 s2, s40, 48
	v_add_u32_e32 v137, s2, v164
	v_ashrrev_i32_e32 v137, 2, v137
	v_med3_i32 v137, v137, 0, s38
	v_lshl_add_u32 v137, v137, 9, v178
	global_load_dwordx4 v[24:27], v137, s[74:75]
	s_add_i32 s2, s40, 56
	v_add_u32_e32 v137, s2, v164
	v_ashrrev_i32_e32 v137, 2, v137
	v_med3_i32 v137, v137, 0, s38
	v_lshl_add_u32 v137, v137, 9, v178
	global_load_dwordx4 v[28:31], v137, s[74:75]
	s_nop 7
	s_add_i32 s77, s40, -64
	s_cmp_lt_u32 s77, s44
	s_cselect_b32 s76, s70, s71
	v_min_f32_e32 v152, s76, v236
	v_min_f32_e32 v153, s76, v237
	v_min_f32_e32 v154, s76, v238
	v_min_f32_e32 v155, s76, v239
	s_waitcnt lgkmcnt(0)
	v_mfma_f32_16x16x32_bf16 v[236:239], v[220:223], v[48:51], 0
	v_mfma_f32_16x16x32_bf16 v[236:239], v[224:227], v[52:55], v[236:239]
	v_mfma_f32_16x16x32_bf16 v[244:247], v[220:223], v[56:59], 0
	v_mfma_f32_16x16x32_bf16 v[244:247], v[224:227], v[60:63], v[244:247]
	s_waitcnt vmcnt(26)
	ds_write_b128 v165, v[32:35]
	ds_write_b128 v165, v[36:39] offset:1152
	ds_read_b128 v[228:231], v175 offset:2304
	ds_read_b128 v[232:235], v175 offset:2368
	v_mul_f32_e32 v152, s72, v152
	v_mul_f32_e32 v153, s72, v153
	v_mul_f32_e32 v154, s72, v154
	v_mul_f32_e32 v155, s72, v155
	v_exp_f32_e32 v152, v152
	v_exp_f32_e32 v153, v153
	v_exp_f32_e32 v154, v154
	v_exp_f32_e32 v155, v155
	v_cndmask_b32_e64 v152, 0, v152, s[54:55]
	v_cndmask_b32_e64 v153, 0, v153, s[56:57]
	v_cndmask_b32_e64 v154, 0, v154, s[58:59]
	v_cndmask_b32_e64 v155, 0, v155, s[60:61]
	v_add_f32_e32 v138, v138, v152
	v_add_f32_e32 v139, v139, v153
	v_add_f32_e32 v138, v138, v154
	v_add_f32_e32 v139, v139, v155
	v_cvt_pk_bf16_f32 v112, v152, v153
	v_cvt_pk_bf16_f32 v113, v154, v155
	s_add_i32 s77, s40, -48
	s_cmp_lt_u32 s77, s44
	s_cselect_b32 s76, s70, s71
	v_min_f32_e32 v152, s76, v240
	v_min_f32_e32 v153, s76, v241
	v_min_f32_e32 v154, s76, v242
	v_min_f32_e32 v155, s76, v243
	v_min_f32_e32 v156, s76, v248
	v_min_f32_e32 v157, s76, v249
	v_min_f32_e32 v158, s76, v250
	v_min_f32_e32 v159, s76, v251
	s_waitcnt lgkmcnt(0)
	v_mfma_f32_16x16x32_bf16 v[240:243], v[228:231], v[48:51], 0
	v_mfma_f32_16x16x32_bf16 v[240:243], v[232:235], v[52:55], v[240:243]
	v_mfma_f32_16x16x32_bf16 v[248:251], v[228:231], v[56:59], 0
	v_mfma_f32_16x16x32_bf16 v[248:251], v[232:235], v[60:63], v[248:251]
	s_waitcnt vmcnt(24)
	ds_write_b128 v165, v[40:43] offset:2304
	ds_write_b128 v165, v[44:47] offset:3456
	ds_read_b128 v[204:207], v175
	ds_read_b128 v[208:211], v175 offset:64
	v_mul_f32_e32 v152, s72, v152
	v_mul_f32_e32 v153, s72, v153
	v_mul_f32_e32 v154, s72, v154
	v_mul_f32_e32 v155, s72, v155
	v_exp_f32_e32 v152, v152
	v_exp_f32_e32 v153, v153
	v_exp_f32_e32 v154, v154
	v_exp_f32_e32 v155, v155
	v_add_f32_e32 v138, v138, v152
	v_add_f32_e32 v139, v139, v153
	v_add_f32_e32 v138, v138, v154
	v_add_f32_e32 v139, v139, v155
	v_cvt_pk_bf16_f32 v114, v152, v153
	v_cvt_pk_bf16_f32 v115, v154, v155
	v_mul_f32_e32 v156, s72, v156
	v_mul_f32_e32 v157, s72, v157
	v_mul_f32_e32 v158, s72, v158
	v_mul_f32_e32 v159, s72, v159
	v_exp_f32_e32 v156, v156
	v_exp_f32_e32 v157, v157
	v_exp_f32_e32 v158, v158
	v_exp_f32_e32 v159, v159
	v_cndmask_b32_e64 v156, 0, v156, s[54:55]
	v_cndmask_b32_e64 v157, 0, v157, s[56:57]
	v_cndmask_b32_e64 v158, 0, v158, s[58:59]
	v_cndmask_b32_e64 v159, 0, v159, s[60:61]
	v_add_f32_e32 v140, v140, v156
	v_add_f32_e32 v141, v141, v157
	v_add_f32_e32 v140, v140, v158
	v_add_f32_e32 v141, v141, v159
	v_cvt_pk_bf16_f32 v186, v156, v157
	v_cvt_pk_bf16_f32 v187, v158, v159
	s_add_i32 s77, s40, -32
	s_cmp_lt_u32 s77, s44
	s_cselect_b32 s76, s70, s71
	v_min_f32_e32 v152, s76, v236
	v_min_f32_e32 v153, s76, v237
	v_min_f32_e32 v154, s76, v238
	v_min_f32_e32 v155, s76, v239
	v_min_f32_e32 v156, s76, v244
	v_min_f32_e32 v157, s76, v245
	v_min_f32_e32 v158, s76, v246
	v_min_f32_e32 v159, s76, v247
	s_waitcnt lgkmcnt(0)
	v_mfma_f32_16x16x32_bf16 v[236:239], v[204:207], v[48:51], 0
	v_mfma_f32_16x16x32_bf16 v[236:239], v[208:211], v[52:55], v[236:239]
	v_mfma_f32_16x16x32_bf16 v[244:247], v[204:207], v[56:59], 0
	v_mfma_f32_16x16x32_bf16 v[244:247], v[208:211], v[60:63], v[244:247]
	s_lshl_b32 s2, s41, s39
	s_lshl_b32 s2, s2, 7
	s_add_u32 s74, s26, s2
	s_addc_u32 s75, s27, 0
	s_add_i32 s2, s40, 64
	v_add_u32_e32 v137, s2, v164
	v_ashrrev_i32_e32 v137, 2, v137
	v_med3_i32 v137, v137, 0, s38
	v_lshl_add_u32 v137, v137, 9, v178
	global_load_dwordx4 v[32:35], v137, s[74:75]
	s_add_i32 s2, s40, 72
	v_add_u32_e32 v137, s2, v164
	v_ashrrev_i32_e32 v137, 2, v137
	v_med3_i32 v137, v137, 0, s38
	v_lshl_add_u32 v137, v137, 9, v178
	global_load_dwordx4 v[36:39], v137, s[74:75]
	s_add_i32 s2, s40, 80
	v_add_u32_e32 v137, s2, v164
	v_ashrrev_i32_e32 v137, 2, v137
	v_med3_i32 v137, v137, 0, s38
	v_lshl_add_u32 v137, v137, 9, v178
	global_load_dwordx4 v[40:43], v137, s[74:75]
	s_add_i32 s2, s40, 88
	v_add_u32_e32 v137, s2, v164
	v_ashrrev_i32_e32 v137, 2, v137
	v_med3_i32 v137, v137, 0, s38
	v_lshl_add_u32 v137, v137, 9, v178
	global_load_dwordx4 v[44:47], v137, s[74:75]
	s_waitcnt vmcnt(14)
	ds_write_b128 v165, v[120:123]
	ds_write_b128 v165, v[124:127] offset:1152
	ds_read_b128 v[212:215], v175 offset:2304
	ds_read_b128 v[216:219], v175 offset:2368
	v_mul_f32_e32 v152, s72, v152
	v_mul_f32_e32 v153, s72, v153
	v_mul_f32_e32 v154, s72, v154
	v_mul_f32_e32 v155, s72, v155
	v_exp_f32_e32 v152, v152
	v_exp_f32_e32 v153, v153
	v_exp_f32_e32 v154, v154
	v_exp_f32_e32 v155, v155
	v_add_f32_e32 v138, v138, v152
	v_add_f32_e32 v139, v139, v153
	v_add_f32_e32 v138, v138, v154
	v_add_f32_e32 v139, v139, v155
	v_cvt_pk_bf16_f32 v116, v152, v153
	v_cvt_pk_bf16_f32 v117, v154, v155
	v_mul_f32_e32 v156, s72, v156
	v_mul_f32_e32 v157, s72, v157
	v_mul_f32_e32 v158, s72, v158
	v_mul_f32_e32 v159, s72, v159
	v_exp_f32_e32 v156, v156
	v_exp_f32_e32 v157, v157
	v_exp_f32_e32 v158, v158
	v_exp_f32_e32 v159, v159
	v_add_f32_e32 v140, v140, v156
	v_add_f32_e32 v141, v141, v157
	v_add_f32_e32 v140, v140, v158
	v_add_f32_e32 v141, v141, v159
	v_cvt_pk_bf16_f32 v188, v156, v157
	v_cvt_pk_bf16_f32 v189, v158, v159
	s_add_i32 s77, s40, -16
	s_cmp_lt_u32 s77, s44
	s_cselect_b32 s76, s70, s71
	v_min_f32_e32 v152, s76, v240
	v_min_f32_e32 v153, s76, v241
	v_min_f32_e32 v154, s76, v242
	v_min_f32_e32 v155, s76, v243
	v_min_f32_e32 v156, s76, v248
	v_min_f32_e32 v157, s76, v249
	v_min_f32_e32 v158, s76, v250
	v_min_f32_e32 v159, s76, v251
	s_waitcnt lgkmcnt(0)
	v_mfma_f32_16x16x32_bf16 v[240:243], v[212:215], v[48:51], 0
	v_mfma_f32_16x16x32_bf16 v[240:243], v[216:219], v[52:55], v[240:243]
	v_mfma_f32_16x16x32_bf16 v[248:251], v[212:215], v[56:59], 0
	v_mfma_f32_16x16x32_bf16 v[248:251], v[216:219], v[60:63], v[248:251]
	s_waitcnt vmcnt(12)
	ds_write_b128 v165, v[192:195] offset:2304
	ds_write_b128 v165, v[196:199] offset:3456
	ds_read_b128 v[220:223], v175
	ds_read_b128 v[224:227], v175 offset:64
	v_mul_f32_e32 v152, s72, v152
	v_mul_f32_e32 v153, s72, v153
	v_mul_f32_e32 v154, s72, v154
	v_mul_f32_e32 v155, s72, v155
	v_exp_f32_e32 v152, v152
	v_exp_f32_e32 v153, v153
	v_exp_f32_e32 v154, v154
	v_exp_f32_e32 v155, v155
	v_add_f32_e32 v138, v138, v152
	v_add_f32_e32 v139, v139, v153
	v_add_f32_e32 v138, v138, v154
	v_add_f32_e32 v139, v139, v155
	v_cvt_pk_bf16_f32 v118, v152, v153
	v_cvt_pk_bf16_f32 v119, v154, v155
	v_mul_f32_e32 v156, s72, v156
	v_mul_f32_e32 v157, s72, v157
	v_mul_f32_e32 v158, s72, v158
	v_mul_f32_e32 v159, s72, v159
	v_exp_f32_e32 v156, v156
	v_exp_f32_e32 v157, v157
	v_exp_f32_e32 v158, v158
	v_exp_f32_e32 v159, v159
	v_add_f32_e32 v140, v140, v156
	v_add_f32_e32 v141, v141, v157
	v_add_f32_e32 v140, v140, v158
	v_add_f32_e32 v141, v141, v159
	v_cvt_pk_bf16_f32 v190, v156, v157
	v_cvt_pk_bf16_f32 v191, v158, v159
	s_add_i32 s77, s40, 0
	s_cmp_lt_u32 s77, s44
	s_cselect_b32 s76, s70, s71
	v_min_f32_e32 v152, s76, v236
	v_min_f32_e32 v153, s76, v237
	v_min_f32_e32 v154, s76, v238
	v_min_f32_e32 v155, s76, v239
	v_min_f32_e32 v156, s76, v244
	v_min_f32_e32 v157, s76, v245
	v_min_f32_e32 v158, s76, v246
	v_min_f32_e32 v159, s76, v247
	s_waitcnt lgkmcnt(0)
	v_mfma_f32_16x16x32_bf16 v[236:239], v[220:223], v[48:51], 0
	v_mfma_f32_16x16x32_bf16 v[236:239], v[224:227], v[52:55], v[236:239]
	v_mfma_f32_16x16x32_bf16 v[244:247], v[220:223], v[56:59], 0
	v_mfma_f32_16x16x32_bf16 v[244:247], v[224:227], v[60:63], v[244:247]
	s_waitcnt vmcnt(10)
	ds_write_b128 v165, v[0:3]
	ds_write_b128 v165, v[4:7] offset:1152
	ds_read_b128 v[228:231], v175 offset:2304
	ds_read_b128 v[232:235], v175 offset:2368
	v_mul_f32_e32 v152, s72, v152
	v_mul_f32_e32 v153, s72, v153
	v_mul_f32_e32 v154, s72, v154
	v_mul_f32_e32 v155, s72, v155
	v_exp_f32_e32 v152, v152
	v_exp_f32_e32 v153, v153
	v_exp_f32_e32 v154, v154
	v_exp_f32_e32 v155, v155
	v_add_f32_e32 v138, v138, v152
	v_add_f32_e32 v139, v139, v153
	v_add_f32_e32 v138, v138, v154
	v_add_f32_e32 v139, v139, v155
	v_cvt_pk_bf16_f32 v120, v152, v153
	v_cvt_pk_bf16_f32 v121, v154, v155
	v_mul_f32_e32 v156, s72, v156
	v_mul_f32_e32 v157, s72, v157
	v_mul_f32_e32 v158, s72, v158
	v_mul_f32_e32 v159, s72, v159
	v_exp_f32_e32 v156, v156
	v_exp_f32_e32 v157, v157
	v_exp_f32_e32 v158, v158
	v_exp_f32_e32 v159, v159
	v_add_f32_e32 v140, v140, v156
	v_add_f32_e32 v141, v141, v157
	v_add_f32_e32 v140, v140, v158
	v_add_f32_e32 v141, v141, v159
	v_cvt_pk_bf16_f32 v192, v156, v157
	v_cvt_pk_bf16_f32 v193, v158, v159
	s_add_i32 s77, s40, 16
	s_cmp_lt_u32 s77, s44
	s_cselect_b32 s76, s70, s71
	v_min_f32_e32 v152, s76, v240
	v_min_f32_e32 v153, s76, v241
	v_min_f32_e32 v154, s76, v242
	v_min_f32_e32 v155, s76, v243
	v_min_f32_e32 v156, s76, v248
	v_min_f32_e32 v157, s76, v249
	v_min_f32_e32 v158, s76, v250
	v_min_f32_e32 v159, s76, v251
	s_waitcnt lgkmcnt(0)
	v_mfma_f32_16x16x32_bf16 v[240:243], v[228:231], v[48:51], 0
	v_mfma_f32_16x16x32_bf16 v[240:243], v[232:235], v[52:55], v[240:243]
	v_mfma_f32_16x16x32_bf16 v[248:251], v[228:231], v[56:59], 0
	v_mfma_f32_16x16x32_bf16 v[248:251], v[232:235], v[60:63], v[248:251]
	s_waitcnt vmcnt(8)
	ds_write_b128 v165, v[8:11] offset:2304
	ds_write_b128 v165, v[12:15] offset:3456
	ds_read_b128 v[204:207], v175
	ds_read_b128 v[208:211], v175 offset:64
	v_mul_f32_e32 v152, s72, v152
	v_mul_f32_e32 v153, s72, v153
	v_mul_f32_e32 v154, s72, v154
	v_mul_f32_e32 v155, s72, v155
	v_exp_f32_e32 v152, v152
	v_exp_f32_e32 v153, v153
	v_exp_f32_e32 v154, v154
	v_exp_f32_e32 v155, v155
	v_add_f32_e32 v138, v138, v152
	v_add_f32_e32 v139, v139, v153
	v_add_f32_e32 v138, v138, v154
	v_add_f32_e32 v139, v139, v155
	v_cvt_pk_bf16_f32 v122, v152, v153
	v_cvt_pk_bf16_f32 v123, v154, v155
	v_mul_f32_e32 v156, s72, v156
	v_mul_f32_e32 v157, s72, v157
	v_mul_f32_e32 v158, s72, v158
	v_mul_f32_e32 v159, s72, v159
	v_exp_f32_e32 v156, v156
	v_exp_f32_e32 v157, v157
	v_exp_f32_e32 v158, v158
	v_exp_f32_e32 v159, v159
	v_add_f32_e32 v140, v140, v156
	v_add_f32_e32 v141, v141, v157
	v_add_f32_e32 v140, v140, v158
	v_add_f32_e32 v141, v141, v159
	v_cvt_pk_bf16_f32 v194, v156, v157
	v_cvt_pk_bf16_f32 v195, v158, v159
	s_add_i32 s77, s40, 32
	s_cmp_lt_u32 s77, s44
	s_cselect_b32 s76, s70, s71
	v_min_f32_e32 v152, s76, v236
	v_min_f32_e32 v153, s76, v237
	v_min_f32_e32 v154, s76, v238
	v_min_f32_e32 v155, s76, v239
	v_min_f32_e32 v156, s76, v244
	v_min_f32_e32 v157, s76, v245
	v_min_f32_e32 v158, s76, v246
	v_min_f32_e32 v159, s76, v247
	s_waitcnt lgkmcnt(0)
	v_mfma_f32_16x16x32_bf16 v[236:239], v[204:207], v[48:51], 0
	v_mfma_f32_16x16x32_bf16 v[236:239], v[208:211], v[52:55], v[236:239]
	v_mfma_f32_16x16x32_bf16 v[244:247], v[204:207], v[56:59], 0
	v_mfma_f32_16x16x32_bf16 v[244:247], v[208:211], v[60:63], v[244:247]
	ds_read_b128 v[212:215], v175 offset:2304
	ds_read_b128 v[216:219], v175 offset:2368
	v_mul_f32_e32 v152, s72, v152
	v_mul_f32_e32 v153, s72, v153
	v_mul_f32_e32 v154, s72, v154
	v_mul_f32_e32 v155, s72, v155
	v_exp_f32_e32 v152, v152
	v_exp_f32_e32 v153, v153
	v_exp_f32_e32 v154, v154
	v_exp_f32_e32 v155, v155
	v_add_f32_e32 v138, v138, v152
	v_add_f32_e32 v139, v139, v153
	v_add_f32_e32 v138, v138, v154
	v_add_f32_e32 v139, v139, v155
	v_cvt_pk_bf16_f32 v124, v152, v153
	v_cvt_pk_bf16_f32 v125, v154, v155
	v_mul_f32_e32 v156, s72, v156
	v_mul_f32_e32 v157, s72, v157
	v_mul_f32_e32 v158, s72, v158
	v_mul_f32_e32 v159, s72, v159
	v_exp_f32_e32 v156, v156
	v_exp_f32_e32 v157, v157
	v_exp_f32_e32 v158, v158
	v_exp_f32_e32 v159, v159
	v_add_f32_e32 v140, v140, v156
	v_add_f32_e32 v141, v141, v157
	v_add_f32_e32 v140, v140, v158
	v_add_f32_e32 v141, v141, v159
	v_cvt_pk_bf16_f32 v196, v156, v157
	v_cvt_pk_bf16_f32 v197, v158, v159
	s_add_i32 s77, s40, 48
	s_cmp_lt_u32 s77, s44
	s_cselect_b32 s76, s70, s71
	v_min_f32_e32 v152, s76, v240
	v_min_f32_e32 v153, s76, v241
	v_min_f32_e32 v154, s76, v242
	v_min_f32_e32 v155, s76, v243
	v_min_f32_e32 v156, s76, v248
	v_min_f32_e32 v157, s76, v249
	v_min_f32_e32 v158, s76, v250
	v_min_f32_e32 v159, s76, v251
	s_waitcnt lgkmcnt(0)
	v_mfma_f32_16x16x32_bf16 v[248:251], v[212:215], v[56:59], 0
	v_mfma_f32_16x16x32_bf16 v[248:251], v[216:219], v[60:63], v[248:251]
	v_mul_f32_e32 v152, s72, v152
	v_mul_f32_e32 v153, s72, v153
	v_mul_f32_e32 v154, s72, v154
	v_mul_f32_e32 v155, s72, v155
	v_exp_f32_e32 v152, v152
	v_exp_f32_e32 v153, v153
	v_exp_f32_e32 v154, v154
	v_exp_f32_e32 v155, v155
	v_add_f32_e32 v138, v138, v152
	v_add_f32_e32 v139, v139, v153
	v_add_f32_e32 v138, v138, v154
	v_add_f32_e32 v139, v139, v155
	v_cvt_pk_bf16_f32 v126, v152, v153
	v_cvt_pk_bf16_f32 v127, v154, v155
	v_mul_f32_e32 v156, s72, v156
	v_mul_f32_e32 v157, s72, v157
	v_mul_f32_e32 v158, s72, v158
	v_mul_f32_e32 v159, s72, v159
	v_exp_f32_e32 v156, v156
	v_exp_f32_e32 v157, v157
	v_exp_f32_e32 v158, v158
	v_exp_f32_e32 v159, v159
	v_add_f32_e32 v140, v140, v156
	v_add_f32_e32 v141, v141, v157
	v_add_f32_e32 v140, v140, v158
	v_add_f32_e32 v141, v141, v159
	v_cvt_pk_bf16_f32 v198, v156, v157
	v_cvt_pk_bf16_f32 v199, v158, v159
	s_add_i32 s77, s40, 64
	s_cmp_lt_u32 s77, s44
	s_cselect_b32 s76, s70, s71
	v_min_f32_e32 v152, s76, v236
	v_min_f32_e32 v153, s76, v237
	v_min_f32_e32 v154, s76, v238
	v_min_f32_e32 v155, s76, v239
	v_min_f32_e32 v156, s76, v244
	v_min_f32_e32 v157, s76, v245
	v_min_f32_e32 v158, s76, v246
	v_min_f32_e32 v159, s76, v247
	v_mul_f32_e32 v152, s72, v152
	v_mul_f32_e32 v153, s72, v153
	v_mul_f32_e32 v154, s72, v154
	v_mul_f32_e32 v155, s72, v155
	v_exp_f32_e32 v152, v152
	v_exp_f32_e32 v153, v153
	v_exp_f32_e32 v154, v154
	v_exp_f32_e32 v155, v155
	v_cndmask_b32_e64 v152, 0, v152, s[62:63]
	v_cndmask_b32_e64 v153, 0, v153, s[64:65]
	v_cndmask_b32_e64 v154, 0, v154, s[66:67]
	v_cndmask_b32_e64 v155, 0, v155, s[68:69]
	v_add_f32_e32 v138, v138, v152
	v_add_f32_e32 v139, v139, v153
	v_add_f32_e32 v138, v138, v154
	v_add_f32_e32 v139, v139, v155
	v_cvt_pk_bf16_f32 v128, v152, v153
	v_cvt_pk_bf16_f32 v129, v154, v155
	v_mul_f32_e32 v156, s72, v156
	v_mul_f32_e32 v157, s72, v157
	v_mul_f32_e32 v158, s72, v158
	v_mul_f32_e32 v159, s72, v159
	v_exp_f32_e32 v156, v156
	v_exp_f32_e32 v157, v157
	v_exp_f32_e32 v158, v158
	v_exp_f32_e32 v159, v159
	v_add_f32_e32 v140, v140, v156
	v_add_f32_e32 v141, v141, v157
	v_add_f32_e32 v140, v140, v158
	v_add_f32_e32 v141, v141, v159
	v_cvt_pk_bf16_f32 v200, v156, v157
	v_cvt_pk_bf16_f32 v201, v158, v159
	s_add_i32 s77, s40, 80
	s_cmp_lt_u32 s77, s44
	s_cselect_b32 s76, s70, s71
	v_min_f32_e32 v156, s76, v248
	v_min_f32_e32 v157, s76, v249
	v_min_f32_e32 v158, s76, v250
	v_min_f32_e32 v159, s76, v251
	v_mul_f32_e32 v156, s72, v156
	v_mul_f32_e32 v157, s72, v157
	v_mul_f32_e32 v158, s72, v158
	v_mul_f32_e32 v159, s72, v159
	v_exp_f32_e32 v156, v156
	v_exp_f32_e32 v157, v157
	v_exp_f32_e32 v158, v158
	v_exp_f32_e32 v159, v159
	v_cndmask_b32_e64 v156, 0, v156, s[62:63]
	v_cndmask_b32_e64 v157, 0, v157, s[64:65]
	v_cndmask_b32_e64 v158, 0, v158, s[66:67]
	v_cndmask_b32_e64 v159, 0, v159, s[68:69]
	v_add_f32_e32 v140, v140, v156
	v_add_f32_e32 v141, v141, v157
	v_add_f32_e32 v140, v140, v158
	v_add_f32_e32 v141, v141, v159
	v_cvt_pk_bf16_f32 v202, v156, v157
	v_cvt_pk_bf16_f32 v203, v158, v159
	v_add_f32_e32 v132, v138, v139
	v_add_f32_e32 v133, v140, v141
	v_add_u32_e32 v134, s42, v160
	v_lshlrev_b32_e32 v134, 4, v134
	v_add_u32_e32 v134, s43, v134
	v_subrev_u32_e32 v135, s15, v134
	v_lshrrev_b32_e32 v136, 4, v135
	v_add_u32_e32 v136, v136, v135
	v_mad_u32_u24 v176, v136, s79, v161
	v_lshl_add_u32 v177, v135, 2, s80
	s_and_b32 s2, s43, 3
	s_lshl_b32 s2, s2, s13
	s_lshr_b32 s3, s43, 2
	s_add_i32 s2, s2, s3
	s_lshl_b32 s2, s2, 7
	s_add_u32 s86, s20, s2
	s_addc_u32 s87, s21, 0
	s_add_i32 s2, s42, -64
	v_add_u32_e32 v136, s2, v164
	v_med3_i32 v136, v136, 0, s14
	v_lshl_add_u32 v136, v136, 9, v162
	global_load_dwordx4 v[0:3], v136, s[86:87]
	s_add_i32 s2, s42, -56
	v_add_u32_e32 v135, s2, v164
	v_med3_i32 v135, v135, 0, s14
	v_lshl_add_u32 v135, v135, 9, v162
	global_load_dwordx4 v[4:7], v135, s[86:87]
	s_add_i32 s2, s42, -48
	v_add_u32_e32 v136, s2, v164
	v_med3_i32 v136, v136, 0, s14
	v_lshl_add_u32 v136, v136, 9, v162
	global_load_dwordx4 v[8:11], v136, s[86:87]
	s_add_i32 s2, s42, -40
	v_add_u32_e32 v135, s2, v164
	v_med3_i32 v135, v135, 0, s14
	v_lshl_add_u32 v135, v135, 9, v162
	global_load_dwordx4 v[12:15], v135, s[86:87]
	ds_bpermute_b32 v142, v167, v132
	ds_bpermute_b32 v143, v167, v133
	ds_write_b128 v165, v[64:67]
	ds_write_b128 v165, v[68:71] offset:1152
	ds_write_b128 v165, v[72:75] offset:2304
	ds_write_b128 v165, v[76:79] offset:3456
	s_waitcnt lgkmcnt(0)
	v_add_f32_e32 v132, v132, v142
	v_add_f32_e32 v133, v133, v143
	ds_bpermute_b32 v142, v168, v132
	ds_bpermute_b32 v143, v168, v133
	ds_read_b64_tr_b16 v[236:237], v166
	ds_read_b64_tr_b16 v[238:239], v166 offset:2304
	ds_read_b64_tr_b16 v[240:241], v166 offset:32
	ds_read_b64_tr_b16 v[242:243], v166 offset:2336
	ds_read_b64_tr_b16 v[244:245], v166 offset:64
	ds_read_b64_tr_b16 v[246:247], v166 offset:2368
	ds_read_b64_tr_b16 v[248:249], v166 offset:96
	ds_read_b64_tr_b16 v[250:251], v166 offset:2400
	s_waitcnt lgkmcnt(0)
	v_add_f32_e32 v132, v132, v142
	v_add_f32_e32 v133, v133, v143
	ds_write_b128 v165, v[80:83]
	ds_write_b128 v165, v[84:87] offset:1152
	ds_write_b128 v165, v[88:91] offset:2304
	ds_write_b128 v165, v[92:95] offset:3456
	v_mfma_f32_16x16x32_bf16 v[204:207], v[236:239], v[112:115], 0
	v_mfma_f32_16x16x32_bf16 v[208:211], v[240:243], v[112:115], 0
	v_mfma_f32_16x16x32_bf16 v[212:215], v[244:247], v[112:115], 0
	v_mfma_f32_16x16x32_bf16 v[216:219], v[248:251], v[112:115], 0
	v_mfma_f32_16x16x32_bf16 v[220:223], v[236:239], v[184:187], 0
	v_mfma_f32_16x16x32_bf16 v[224:227], v[240:243], v[184:187], 0
	v_mfma_f32_16x16x32_bf16 v[228:231], v[244:247], v[184:187], 0
	v_mfma_f32_16x16x32_bf16 v[232:235], v[248:251], v[184:187], 0
	s_waitcnt lgkmcnt(0)
	ds_read_b64_tr_b16 v[236:237], v166
	ds_read_b64_tr_b16 v[238:239], v166 offset:2304
	ds_read_b64_tr_b16 v[240:241], v166 offset:32
	ds_read_b64_tr_b16 v[242:243], v166 offset:2336
	ds_read_b64_tr_b16 v[244:245], v166 offset:64
	ds_read_b64_tr_b16 v[246:247], v166 offset:2368
	ds_read_b64_tr_b16 v[248:249], v166 offset:96
	ds_read_b64_tr_b16 v[250:251], v166 offset:2400
	s_waitcnt lgkmcnt(0)
	ds_write_b128 v165, v[96:99]
	ds_write_b128 v165, v[100:103] offset:1152
	ds_write_b128 v165, v[104:107] offset:2304
	ds_write_b128 v165, v[108:111] offset:3456
	v_mfma_f32_16x16x32_bf16 v[204:207], v[236:239], v[116:119], v[204:207]
	v_mfma_f32_16x16x32_bf16 v[208:211], v[240:243], v[116:119], v[208:211]
	v_mfma_f32_16x16x32_bf16 v[212:215], v[244:247], v[116:119], v[212:215]
	v_mfma_f32_16x16x32_bf16 v[216:219], v[248:251], v[116:119], v[216:219]
	v_mfma_f32_16x16x32_bf16 v[220:223], v[236:239], v[188:191], v[220:223]
	v_mfma_f32_16x16x32_bf16 v[224:227], v[240:243], v[188:191], v[224:227]
	v_mfma_f32_16x16x32_bf16 v[228:231], v[244:247], v[188:191], v[228:231]
	v_mfma_f32_16x16x32_bf16 v[232:235], v[248:251], v[188:191], v[232:235]
	s_waitcnt lgkmcnt(0)
	ds_read_b64_tr_b16 v[236:237], v166
	ds_read_b64_tr_b16 v[238:239], v166 offset:2304
	ds_read_b64_tr_b16 v[240:241], v166 offset:32
	ds_read_b64_tr_b16 v[242:243], v166 offset:2336
	ds_read_b64_tr_b16 v[244:245], v166 offset:64
	ds_read_b64_tr_b16 v[246:247], v166 offset:2368
	ds_read_b64_tr_b16 v[248:249], v166 offset:96
	ds_read_b64_tr_b16 v[250:251], v166 offset:2400
	s_waitcnt lgkmcnt(0)
	s_waitcnt vmcnt(8)
	ds_write_b128 v165, v[16:19]
	ds_write_b128 v165, v[20:23] offset:1152
	ds_write_b128 v165, v[24:27] offset:2304
	ds_write_b128 v165, v[28:31] offset:3456
	v_mfma_f32_16x16x32_bf16 v[204:207], v[236:239], v[120:123], v[204:207]
	v_mfma_f32_16x16x32_bf16 v[208:211], v[240:243], v[120:123], v[208:211]
	v_mfma_f32_16x16x32_bf16 v[212:215], v[244:247], v[120:123], v[212:215]
	v_mfma_f32_16x16x32_bf16 v[216:219], v[248:251], v[120:123], v[216:219]
	v_mfma_f32_16x16x32_bf16 v[220:223], v[236:239], v[192:195], v[220:223]
	v_mfma_f32_16x16x32_bf16 v[224:227], v[240:243], v[192:195], v[224:227]
	v_mfma_f32_16x16x32_bf16 v[228:231], v[244:247], v[192:195], v[228:231]
	v_mfma_f32_16x16x32_bf16 v[232:235], v[248:251], v[192:195], v[232:235]
	s_waitcnt lgkmcnt(0)
	ds_read_b64_tr_b16 v[236:237], v166
	ds_read_b64_tr_b16 v[238:239], v166 offset:2304
	ds_read_b64_tr_b16 v[240:241], v166 offset:32
	ds_read_b64_tr_b16 v[242:243], v166 offset:2336
	ds_read_b64_tr_b16 v[244:245], v166 offset:64
	ds_read_b64_tr_b16 v[246:247], v166 offset:2368
	ds_read_b64_tr_b16 v[248:249], v166 offset:96
	ds_read_b64_tr_b16 v[250:251], v166 offset:2400
	s_waitcnt lgkmcnt(0)
	s_add_i32 s2, s42, -32
	v_add_u32_e32 v136, s2, v164
	v_med3_i32 v136, v136, 0, s14
	v_lshl_add_u32 v136, v136, 9, v162
	global_load_dwordx4 v[16:19], v136, s[86:87]
	s_add_i32 s2, s42, -24
	v_add_u32_e32 v135, s2, v164
	v_med3_i32 v135, v135, 0, s14
	v_lshl_add_u32 v135, v135, 9, v162
	global_load_dwordx4 v[20:23], v135, s[86:87]
	s_add_i32 s2, s42, -16
	v_add_u32_e32 v136, s2, v164
	v_med3_i32 v136, v136, 0, s14
	v_lshl_add_u32 v136, v136, 9, v162
	global_load_dwordx4 v[24:27], v136, s[86:87]
	s_add_i32 s2, s42, -8
	v_add_u32_e32 v135, s2, v164
	v_med3_i32 v135, v135, 0, s14
	v_lshl_add_u32 v135, v135, 9, v162
	global_load_dwordx4 v[28:31], v135, s[86:87]
	s_waitcnt vmcnt(8)
	ds_write_b128 v165, v[32:35]
	ds_write_b128 v165, v[36:39] offset:1152
	ds_write_b128 v165, v[40:43] offset:2304
	ds_write_b128 v165, v[44:47] offset:3456
	v_mfma_f32_16x16x32_bf16 v[204:207], v[236:239], v[124:127], v[204:207]
	v_mfma_f32_16x16x32_bf16 v[208:211], v[240:243], v[124:127], v[208:211]
	v_mfma_f32_16x16x32_bf16 v[212:215], v[244:247], v[124:127], v[212:215]
	v_mfma_f32_16x16x32_bf16 v[216:219], v[248:251], v[124:127], v[216:219]
	v_mfma_f32_16x16x32_bf16 v[220:223], v[236:239], v[196:199], v[220:223]
	v_mfma_f32_16x16x32_bf16 v[224:227], v[240:243], v[196:199], v[224:227]
	v_mfma_f32_16x16x32_bf16 v[228:231], v[244:247], v[196:199], v[228:231]
	v_mfma_f32_16x16x32_bf16 v[232:235], v[248:251], v[196:199], v[232:235]
	s_waitcnt lgkmcnt(0)
	ds_read_b64_tr_b16 v[236:237], v166
	ds_read_b64_tr_b16 v[238:239], v166 offset:2304
	ds_read_b64_tr_b16 v[240:241], v166 offset:32
	ds_read_b64_tr_b16 v[242:243], v166 offset:2336
	ds_read_b64_tr_b16 v[244:245], v166 offset:64
	ds_read_b64_tr_b16 v[246:247], v166 offset:2368
	ds_read_b64_tr_b16 v[248:249], v166 offset:96
	ds_read_b64_tr_b16 v[250:251], v166 offset:2400
	s_waitcnt lgkmcnt(0)
	s_add_i32 s2, s42, 0
	v_add_u32_e32 v136, s2, v164
	v_med3_i32 v136, v136, 0, s14
	v_lshl_add_u32 v136, v136, 9, v162
	global_load_dwordx4 v[32:35], v136, s[86:87]
	s_add_i32 s2, s42, 8
	v_add_u32_e32 v135, s2, v164
	v_med3_i32 v135, v135, 0, s14
	v_lshl_add_u32 v135, v135, 9, v162
	global_load_dwordx4 v[36:39], v135, s[86:87]
	s_add_i32 s2, s42, 16
	v_add_u32_e32 v136, s2, v164
	v_med3_i32 v136, v136, 0, s14
	v_lshl_add_u32 v136, v136, 9, v162
	global_load_dwordx4 v[40:43], v136, s[86:87]
	s_add_i32 s2, s42, 24
	v_add_u32_e32 v135, s2, v164
	v_med3_i32 v135, v135, 0, s14
	v_lshl_add_u32 v135, v135, 9, v162
	global_load_dwordx4 v[44:47], v135, s[86:87]
	v_mfma_f32_16x16x32_bf16 v[204:207], v[236:239], v[128:131], v[204:207]
	v_mfma_f32_16x16x32_bf16 v[208:211], v[240:243], v[128:131], v[208:211]
	v_mfma_f32_16x16x32_bf16 v[212:215], v[244:247], v[128:131], v[212:215]
	v_mfma_f32_16x16x32_bf16 v[216:219], v[248:251], v[128:131], v[216:219]
	v_mfma_f32_16x16x32_bf16 v[220:223], v[236:239], v[200:203], v[220:223]
	v_mfma_f32_16x16x32_bf16 v[224:227], v[240:243], v[200:203], v[224:227]
	v_mfma_f32_16x16x32_bf16 v[228:231], v[244:247], v[200:203], v[228:231]
	v_mfma_f32_16x16x32_bf16 v[232:235], v[248:251], v[200:203], v[232:235]
	s_add_i32 s2, s42, 32
	v_add_u32_e32 v136, s2, v164
	v_med3_i32 v136, v136, 0, s14
	v_lshl_add_u32 v136, v136, 9, v162
	global_load_dwordx4 v[120:123], v136, s[86:87]
	s_add_i32 s2, s42, 40
	v_add_u32_e32 v135, s2, v164
	v_med3_i32 v135, v135, 0, s14
	v_lshl_add_u32 v135, v135, 9, v162
	global_load_dwordx4 v[124:127], v135, s[86:87]
	s_add_i32 s2, s42, 48
	v_add_u32_e32 v136, s2, v164
	v_med3_i32 v136, v136, 0, s14
	v_lshl_add_u32 v136, v136, 9, v162
	global_load_dwordx4 v[192:195], v136, s[86:87]
	s_add_i32 s2, s42, 56
	v_add_u32_e32 v135, s2, v164
	v_med3_i32 v135, v135, 0, s14
	v_lshl_add_u32 v135, v135, 9, v162
	global_load_dwordx4 v[196:199], v135, s[86:87]
	s_and_b32 s2, s43, 3
	s_lshl_b32 s2, s2, s13
	s_lshr_b32 s3, s43, 2
	s_add_i32 s2, s2, s3
	s_lshl_b32 s2, s2, 7
	s_add_u32 s74, s22, s2
	s_addc_u32 s75, s23, 0
	s_add_i32 s2, s42, -64
	v_add_u32_e32 v137, s2, v164
	v_med3_i32 v137, v137, 0, s14
	v_lshl_add_u32 v137, v137, 9, v162
	global_load_dwordx4 v[64:67], v137, s[74:75]
	s_add_i32 s2, s42, -56
	v_add_u32_e32 v137, s2, v164
	v_med3_i32 v137, v137, 0, s14
	v_lshl_add_u32 v137, v137, 9, v162
	global_load_dwordx4 v[68:71], v137, s[74:75]
	s_add_i32 s2, s42, -48
	v_add_u32_e32 v137, s2, v164
	v_med3_i32 v137, v137, 0, s14
	v_lshl_add_u32 v137, v137, 9, v162
	global_load_dwordx4 v[72:75], v137, s[74:75]
	s_add_i32 s2, s42, -40
	v_add_u32_e32 v137, s2, v164
	v_med3_i32 v137, v137, 0, s14
	v_lshl_add_u32 v137, v137, 9, v162
	global_load_dwordx4 v[76:79], v137, s[74:75]
	s_and_b32 s2, s43, 3
	s_lshl_b32 s2, s2, s13
	s_lshr_b32 s3, s43, 2
	s_add_i32 s2, s2, s3
	s_lshl_b32 s2, s2, 7
	s_add_u32 s74, s22, s2
	s_addc_u32 s75, s23, 0
	s_add_i32 s2, s42, -32
	v_add_u32_e32 v137, s2, v164
	v_med3_i32 v137, v137, 0, s14
	v_lshl_add_u32 v137, v137, 9, v162
	global_load_dwordx4 v[80:83], v137, s[74:75]
	s_add_i32 s2, s42, -24
	v_add_u32_e32 v137, s2, v164
	v_med3_i32 v137, v137, 0, s14
	v_lshl_add_u32 v137, v137, 9, v162
	global_load_dwordx4 v[84:87], v137, s[74:75]
	s_add_i32 s2, s42, -16
	v_add_u32_e32 v137, s2, v164
	v_med3_i32 v137, v137, 0, s14
	v_lshl_add_u32 v137, v137, 9, v162
	global_load_dwordx4 v[88:91], v137, s[74:75]
	s_add_i32 s2, s42, -8
	v_add_u32_e32 v137, s2, v164
	v_med3_i32 v137, v137, 0, s14
	v_lshl_add_u32 v137, v137, 9, v162
	global_load_dwordx4 v[92:95], v137, s[74:75]
	s_and_b32 s2, s43, 3
	s_lshl_b32 s2, s2, s13
	s_lshr_b32 s3, s43, 2
	s_add_i32 s2, s2, s3
	s_lshl_b32 s2, s2, 7
	s_add_u32 s74, s22, s2
	s_addc_u32 s75, s23, 0
	s_add_i32 s2, s42, 0
	v_add_u32_e32 v137, s2, v164
	v_med3_i32 v137, v137, 0, s14
	v_lshl_add_u32 v137, v137, 9, v162
	global_load_dwordx4 v[96:99], v137, s[74:75]
	s_add_i32 s2, s42, 8
	v_add_u32_e32 v137, s2, v164
	v_med3_i32 v137, v137, 0, s14
	v_lshl_add_u32 v137, v137, 9, v162
	global_load_dwordx4 v[100:103], v137, s[74:75]
	s_add_i32 s2, s42, 16
	v_add_u32_e32 v137, s2, v164
	v_med3_i32 v137, v137, 0, s14
	v_lshl_add_u32 v137, v137, 9, v162
	global_load_dwordx4 v[104:107], v137, s[74:75]
	s_add_i32 s2, s42, 24
	v_add_u32_e32 v137, s2, v164
	v_med3_i32 v137, v137, 0, s14
	v_lshl_add_u32 v137, v137, 9, v162
	global_load_dwordx4 v[108:111], v137, s[74:75]
	s_waitcnt lgkmcnt(0)
	s_barrier
	ds_read_b128 v[236:239], v173 offset:0
	ds_read_b128 v[240:243], v173 offset:64
	ds_read_b128 v[244:247], v173 offset:128
	ds_read_b128 v[248:251], v173 offset:192
	ds_read_b32 v142, v174 offset:0
	s_waitcnt lgkmcnt(0)
	v_add_f32_e32 v204, v236, v204
	v_add_f32_e32 v205, v237, v205
	v_add_f32_e32 v206, v238, v206
	v_add_f32_e32 v207, v239, v207
	v_add_f32_e32 v208, v240, v208
	v_add_f32_e32 v209, v241, v209
	v_add_f32_e32 v210, v242, v210
	v_add_f32_e32 v211, v243, v211
	v_add_f32_e32 v212, v244, v212
	v_add_f32_e32 v213, v245, v213
	v_add_f32_e32 v214, v246, v214
	v_add_f32_e32 v215, v247, v215
	v_add_f32_e32 v216, v248, v216
	v_add_f32_e32 v217, v249, v217
	v_add_f32_e32 v218, v250, v218
	v_add_f32_e32 v219, v251, v219
	v_add_f32_e32 v132, v142, v132
	ds_write_b128 v173, v[204:207] offset:0
	ds_write_b128 v173, v[208:211] offset:64
	ds_write_b128 v173, v[212:215] offset:128
	ds_write_b128 v173, v[216:219] offset:192
	ds_write_b32 v174, v132 offset:0
	ds_read_b128 v[236:239], v173 offset:18496
	ds_read_b128 v[240:243], v173 offset:18560
	ds_read_b128 v[244:247], v173 offset:18624
	ds_read_b128 v[248:251], v173 offset:18688
	ds_read_b32 v142, v174 offset:256
	s_waitcnt lgkmcnt(0)
	v_add_f32_e32 v220, v236, v220
	v_add_f32_e32 v221, v237, v221
	v_add_f32_e32 v222, v238, v222
	v_add_f32_e32 v223, v239, v223
	v_add_f32_e32 v224, v240, v224
	v_add_f32_e32 v225, v241, v225
	v_add_f32_e32 v226, v242, v226
	v_add_f32_e32 v227, v243, v227
	v_add_f32_e32 v228, v244, v228
	v_add_f32_e32 v229, v245, v229
	v_add_f32_e32 v230, v246, v230
	v_add_f32_e32 v231, v247, v231
	v_add_f32_e32 v232, v248, v232
	v_add_f32_e32 v233, v249, v233
	v_add_f32_e32 v234, v250, v234
	v_add_f32_e32 v235, v251, v235
	v_add_f32_e32 v133, v142, v133
	ds_write_b128 v173, v[220:223] offset:18496
	ds_write_b128 v173, v[224:227] offset:18560
	ds_write_b128 v173, v[228:231] offset:18624
	ds_write_b128 v173, v[232:235] offset:18688
	ds_write_b32 v174, v133 offset:256
	s_mov_b32 s40, s42
	s_mov_b32 s41, s43
	v_mov_b32_e32 v173, v176
	v_mov_b32_e32 v174, v177
	s_lshr_b32 s44, s33, 4
	s_lshr_b32 s42, s15, 4
	s_add_i32 s43, s0, 8
	v_subrev_u32_e32 v143, s80, v174
	v_lshl_add_u32 v143, v143, 5, v161
	v_add_u32_e32 v143, 0x1b500, v143
	ds_read_b128 v[48:51], v143
	ds_read_b128 v[52:55], v143 offset:64
	s_waitcnt lgkmcnt(0)
	v_mov_b32_e32 v138, 0
	v_mov_b32_e32 v139, 0
	s_waitcnt vmcnt(24)
	ds_write_b128 v165, v[0:3]
	ds_write_b128 v165, v[4:7] offset:1152
	ds_write_b128 v165, v[8:11] offset:2304
	ds_write_b128 v165, v[12:15] offset:3456
	s_waitcnt lgkmcnt(0)
	ds_read_b128 v[204:207], v175
	ds_read_b128 v[208:211], v175 offset:64
	ds_read_b128 v[212:215], v175 offset:2304
	ds_read_b128 v[216:219], v175 offset:2368
	s_and_b32 s2, s41, 3
	s_lshl_b32 s2, s2, s39
	s_lshr_b32 s3, s41, 2
	s_add_i32 s2, s2, s3
	s_lshl_b32 s2, s2, 7
	s_add_u32 s86, s24, s2
	s_addc_u32 s87, s25, 0
	s_add_i32 s2, s40, 64
	v_add_u32_e32 v136, s2, v164
	v_med3_i32 v136, v136, 0, s38
	v_lshl_add_u32 v136, v136, 9, v162
	global_load_dwordx4 v[0:3], v136, s[86:87]
	s_add_i32 s2, s40, 72
	v_add_u32_e32 v135, s2, v164
	v_med3_i32 v135, v135, 0, s38
	v_lshl_add_u32 v135, v135, 9, v162
	global_load_dwordx4 v[4:7], v135, s[86:87]
	s_waitcnt vmcnt(22)
	s_waitcnt lgkmcnt(0)
	ds_write_b128 v165, v[16:19]
	ds_write_b128 v165, v[20:23] offset:1152
	ds_write_b128 v165, v[24:27] offset:2304
	ds_write_b128 v165, v[28:31] offset:3456
	v_mfma_f32_16x16x32_bf16 v[236:239], v[204:207], v[48:51], 0
	v_mfma_f32_16x16x32_bf16 v[236:239], v[208:211], v[52:55], v[236:239]
	v_mfma_f32_16x16x32_bf16 v[240:243], v[212:215], v[48:51], 0
	v_mfma_f32_16x16x32_bf16 v[240:243], v[216:219], v[52:55], v[240:243]
	s_waitcnt lgkmcnt(0)
	ds_read_b128 v[220:223], v175
	ds_read_b128 v[224:227], v175 offset:64
	s_and_b32 s2, s41, 3
	s_lshl_b32 s2, s2, s39
	s_lshr_b32 s3, s41, 2
	s_add_i32 s2, s2, s3
	s_lshl_b32 s2, s2, 7
	s_add_u32 s74, s26, s2
	s_addc_u32 s75, s27, 0
	s_add_i32 s2, s40, 32
	v_add_u32_e32 v137, s2, v164
	v_med3_i32 v137, v137, 0, s38
	v_lshl_add_u32 v137, v137, 9, v162
	global_load_dwordx4 v[16:19], v137, s[74:75]
	s_add_i32 s2, s40, 40
	v_add_u32_e32 v137, s2, v164
	v_med3_i32 v137, v137, 0, s38
	v_lshl_add_u32 v137, v137, 9, v162
	global_load_dwordx4 v[20:23], v137, s[74:75]
	s_add_i32 s2, s40, 48
	v_add_u32_e32 v137, s2, v164
	v_med3_i32 v137, v137, 0, s38
	v_lshl_add_u32 v137, v137, 9, v162
	global_load_dwordx4 v[24:27], v137, s[74:75]
	s_add_i32 s2, s40, 56
	v_add_u32_e32 v137, s2, v164
	v_med3_i32 v137, v137, 0, s38
	v_lshl_add_u32 v137, v137, 9, v162
	global_load_dwordx4 v[28:31], v137, s[74:75]
	s_nop 7
	s_add_i32 s77, s40, -64
	s_cmp_lt_u32 s77, s44
	s_cselect_b32 s76, s70, s71
	v_min_f32_e32 v152, s76, v236
	v_min_f32_e32 v153, s76, v237
	v_min_f32_e32 v154, s76, v238
	v_min_f32_e32 v155, s76, v239
	s_waitcnt lgkmcnt(0)
	v_mfma_f32_16x16x32_bf16 v[236:239], v[220:223], v[48:51], 0
	v_mfma_f32_16x16x32_bf16 v[236:239], v[224:227], v[52:55], v[236:239]
	s_waitcnt vmcnt(24)
	ds_write_b128 v165, v[32:35]
	ds_write_b128 v165, v[36:39] offset:1152
	ds_read_b128 v[228:231], v175 offset:2304
	ds_read_b128 v[232:235], v175 offset:2368
	v_mul_f32_e32 v152, s72, v152
	v_mul_f32_e32 v153, s72, v153
	v_mul_f32_e32 v154, s72, v154
	v_mul_f32_e32 v155, s72, v155
	v_exp_f32_e32 v152, v152
	v_exp_f32_e32 v153, v153
	v_exp_f32_e32 v154, v154
	v_exp_f32_e32 v155, v155
	v_cndmask_b32_e64 v152, 0, v152, s[54:55]
	v_cndmask_b32_e64 v153, 0, v153, s[56:57]
	v_cndmask_b32_e64 v154, 0, v154, s[58:59]
	v_cndmask_b32_e64 v155, 0, v155, s[60:61]
	v_add_f32_e32 v138, v138, v152
	v_add_f32_e32 v139, v139, v153
	v_add_f32_e32 v138, v138, v154
	v_add_f32_e32 v139, v139, v155
	v_cvt_pk_bf16_f32 v112, v152, v153
	v_cvt_pk_bf16_f32 v113, v154, v155
	s_add_i32 s77, s40, -48
	s_cmp_lt_u32 s77, s44
	s_cselect_b32 s76, s70, s71
	v_min_f32_e32 v152, s76, v240
	v_min_f32_e32 v153, s76, v241
	v_min_f32_e32 v154, s76, v242
	v_min_f32_e32 v155, s76, v243
	s_waitcnt lgkmcnt(0)
	v_mfma_f32_16x16x32_bf16 v[240:243], v[228:231], v[48:51], 0
	v_mfma_f32_16x16x32_bf16 v[240:243], v[232:235], v[52:55], v[240:243]
	s_waitcnt vmcnt(22)
	ds_write_b128 v165, v[40:43] offset:2304
	ds_write_b128 v165, v[44:47] offset:3456
	ds_read_b128 v[204:207], v175
	ds_read_b128 v[208:211], v175 offset:64
	v_mul_f32_e32 v152, s72, v152
	v_mul_f32_e32 v153, s72, v153
	v_mul_f32_e32 v154, s72, v154
	v_mul_f32_e32 v155, s72, v155
	v_exp_f32_e32 v152, v152
	v_exp_f32_e32 v153, v153
	v_exp_f32_e32 v154, v154
	v_exp_f32_e32 v155, v155
	v_add_f32_e32 v138, v138, v152
	v_add_f32_e32 v139, v139, v153
	v_add_f32_e32 v138, v138, v154
	v_add_f32_e32 v139, v139, v155
	v_cvt_pk_bf16_f32 v114, v152, v153
	v_cvt_pk_bf16_f32 v115, v154, v155
	s_add_i32 s77, s40, -32
	s_cmp_lt_u32 s77, s44
	s_cselect_b32 s76, s70, s71
	v_min_f32_e32 v152, s76, v236
	v_min_f32_e32 v153, s76, v237
	v_min_f32_e32 v154, s76, v238
	v_min_f32_e32 v155, s76, v239
	s_waitcnt lgkmcnt(0)
	v_mfma_f32_16x16x32_bf16 v[236:239], v[204:207], v[48:51], 0
	v_mfma_f32_16x16x32_bf16 v[236:239], v[208:211], v[52:55], v[236:239]
	s_and_b32 s2, s41, 3
	s_lshl_b32 s2, s2, s39
	s_lshr_b32 s3, s41, 2
	s_add_i32 s2, s2, s3
	s_lshl_b32 s2, s2, 7
	s_add_u32 s74, s26, s2
	s_addc_u32 s75, s27, 0
	s_add_i32 s2, s40, 64
	v_add_u32_e32 v137, s2, v164
	v_med3_i32 v137, v137, 0, s38
	v_lshl_add_u32 v137, v137, 9, v162
	global_load_dwordx4 v[32:35], v137, s[74:75]
	s_add_i32 s2, s40, 72
	v_add_u32_e32 v137, s2, v164
	v_med3_i32 v137, v137, 0, s38
	v_lshl_add_u32 v137, v137, 9, v162
	global_load_dwordx4 v[36:39], v137, s[74:75]
	s_waitcnt vmcnt(22)
	ds_write_b128 v165, v[120:123]
	ds_write_b128 v165, v[124:127] offset:1152
	ds_read_b128 v[212:215], v175 offset:2304
	ds_read_b128 v[216:219], v175 offset:2368
	v_mul_f32_e32 v152, s72, v152
	v_mul_f32_e32 v153, s72, v153
	v_mul_f32_e32 v154, s72, v154
	v_mul_f32_e32 v155, s72, v155
	v_exp_f32_e32 v152, v152
	v_exp_f32_e32 v153, v153
	v_exp_f32_e32 v154, v154
	v_exp_f32_e32 v155, v155
	v_add_f32_e32 v138, v138, v152
	v_add_f32_e32 v139, v139, v153
	v_add_f32_e32 v138, v138, v154
	v_add_f32_e32 v139, v139, v155
	v_cvt_pk_bf16_f32 v116, v152, v153
	v_cvt_pk_bf16_f32 v117, v154, v155
	s_add_i32 s77, s40, -16
	s_cmp_lt_u32 s77, s44
	s_cselect_b32 s76, s70, s71
	v_min_f32_e32 v152, s76, v240
	v_min_f32_e32 v153, s76, v241
	v_min_f32_e32 v154, s76, v242
	v_min_f32_e32 v155, s76, v243
	s_waitcnt lgkmcnt(0)
	v_mfma_f32_16x16x32_bf16 v[240:243], v[212:215], v[48:51], 0
	v_mfma_f32_16x16x32_bf16 v[240:243], v[216:219], v[52:55], v[240:243]
	s_waitcnt vmcnt(20)
	ds_write_b128 v165, v[192:195] offset:2304
	ds_write_b128 v165, v[196:199] offset:3456
	ds_read_b128 v[220:223], v175
	ds_read_b128 v[224:227], v175 offset:64
	v_mul_f32_e32 v152, s72, v152
	v_mul_f32_e32 v153, s72, v153
	v_mul_f32_e32 v154, s72, v154
	v_mul_f32_e32 v155, s72, v155
	v_exp_f32_e32 v152, v152
	v_exp_f32_e32 v153, v153
	v_exp_f32_e32 v154, v154
	v_exp_f32_e32 v155, v155
	v_add_f32_e32 v138, v138, v152
	v_add_f32_e32 v139, v139, v153
	v_add_f32_e32 v138, v138, v154
	v_add_f32_e32 v139, v139, v155
	v_cvt_pk_bf16_f32 v118, v152, v153
	v_cvt_pk_bf16_f32 v119, v154, v155
	s_add_i32 s77, s40, 0
	s_cmp_lt_u32 s77, s44
	s_cselect_b32 s76, s70, s71
	v_min_f32_e32 v152, s76, v236
	v_min_f32_e32 v153, s76, v237
	v_min_f32_e32 v154, s76, v238
	v_min_f32_e32 v155, s76, v239
	s_waitcnt lgkmcnt(0)
	v_mfma_f32_16x16x32_bf16 v[236:239], v[220:223], v[48:51], 0
	v_mfma_f32_16x16x32_bf16 v[236:239], v[224:227], v[52:55], v[236:239]
	s_waitcnt vmcnt(6)
	ds_write_b128 v165, v[0:3]
	ds_write_b128 v165, v[4:7] offset:1152
	ds_read_b128 v[228:231], v175 offset:2304
	ds_read_b128 v[232:235], v175 offset:2368
	v_mul_f32_e32 v152, s72, v152
	v_mul_f32_e32 v153, s72, v153
	v_mul_f32_e32 v154, s72, v154
	v_mul_f32_e32 v155, s72, v155
	v_exp_f32_e32 v152, v152
	v_exp_f32_e32 v153, v153
	v_exp_f32_e32 v154, v154
	v_exp_f32_e32 v155, v155
	v_add_f32_e32 v138, v138, v152
	v_add_f32_e32 v139, v139, v153
	v_add_f32_e32 v138, v138, v154
	v_add_f32_e32 v139, v139, v155
	v_cvt_pk_bf16_f32 v120, v152, v153
	v_cvt_pk_bf16_f32 v121, v154, v155
	s_add_i32 s77, s40, 16
	s_cmp_lt_u32 s77, s44
	s_cselect_b32 s76, s70, s71
	v_min_f32_e32 v152, s76, v240
	v_min_f32_e32 v153, s76, v241
	v_min_f32_e32 v154, s76, v242
	v_min_f32_e32 v155, s76, v243
	s_waitcnt lgkmcnt(0)
	v_mfma_f32_16x16x32_bf16 v[240:243], v[228:231], v[48:51], 0
	v_mfma_f32_16x16x32_bf16 v[240:243], v[232:235], v[52:55], v[240:243]
	ds_read_b128 v[204:207], v175
	ds_read_b128 v[208:211], v175 offset:64
	v_mul_f32_e32 v152, s72, v152
	v_mul_f32_e32 v153, s72, v153
	v_mul_f32_e32 v154, s72, v154
	v_mul_f32_e32 v155, s72, v155
	v_exp_f32_e32 v152, v152
	v_exp_f32_e32 v153, v153
	v_exp_f32_e32 v154, v154
	v_exp_f32_e32 v155, v155
	v_add_f32_e32 v138, v138, v152
	v_add_f32_e32 v139, v139, v153
	v_add_f32_e32 v138, v138, v154
	v_add_f32_e32 v139, v139, v155
	v_cvt_pk_bf16_f32 v122, v152, v153
	v_cvt_pk_bf16_f32 v123, v154, v155
	s_add_i32 s77, s40, 32
	s_cmp_lt_u32 s77, s44
	s_cselect_b32 s76, s70, s71
	v_min_f32_e32 v152, s76, v236
	v_min_f32_e32 v153, s76, v237
	v_min_f32_e32 v154, s76, v238
	v_min_f32_e32 v155, s76, v239
	s_waitcnt lgkmcnt(0)
	v_mfma_f32_16x16x32_bf16 v[236:239], v[204:207], v[48:51], 0
	v_mfma_f32_16x16x32_bf16 v[236:239], v[208:211], v[52:55], v[236:239]
	v_mul_f32_e32 v152, s72, v152
	v_mul_f32_e32 v153, s72, v153
	v_mul_f32_e32 v154, s72, v154
	v_mul_f32_e32 v155, s72, v155
	v_exp_f32_e32 v152, v152
	v_exp_f32_e32 v153, v153
	v_exp_f32_e32 v154, v154
	v_exp_f32_e32 v155, v155
	v_add_f32_e32 v138, v138, v152
	v_add_f32_e32 v139, v139, v153
	v_add_f32_e32 v138, v138, v154
	v_add_f32_e32 v139, v139, v155
	v_cvt_pk_bf16_f32 v124, v152, v153
	v_cvt_pk_bf16_f32 v125, v154, v155
	s_add_i32 s77, s40, 48
	s_cmp_lt_u32 s77, s44
	s_cselect_b32 s76, s70, s71
	v_min_f32_e32 v152, s76, v240
	v_min_f32_e32 v153, s76, v241
	v_min_f32_e32 v154, s76, v242
	v_min_f32_e32 v155, s76, v243
	v_mul_f32_e32 v152, s72, v152
	v_mul_f32_e32 v153, s72, v153
	v_mul_f32_e32 v154, s72, v154
	v_mul_f32_e32 v155, s72, v155
	v_exp_f32_e32 v152, v152
	v_exp_f32_e32 v153, v153
	v_exp_f32_e32 v154, v154
	v_exp_f32_e32 v155, v155
	v_add_f32_e32 v138, v138, v152
	v_add_f32_e32 v139, v139, v153
	v_add_f32_e32 v138, v138, v154
	v_add_f32_e32 v139, v139, v155
	v_cvt_pk_bf16_f32 v126, v152, v153
	v_cvt_pk_bf16_f32 v127, v154, v155
	s_add_i32 s77, s40, 64
	s_cmp_lt_u32 s77, s44
	s_cselect_b32 s76, s70, s71
	v_min_f32_e32 v152, s76, v236
	v_min_f32_e32 v153, s76, v237
	v_min_f32_e32 v154, s76, v238
	v_min_f32_e32 v155, s76, v239
	v_mul_f32_e32 v152, s72, v152
	v_mul_f32_e32 v153, s72, v153
	v_mul_f32_e32 v154, s72, v154
	v_mul_f32_e32 v155, s72, v155
	v_exp_f32_e32 v152, v152
	v_exp_f32_e32 v153, v153
	v_exp_f32_e32 v154, v154
	v_exp_f32_e32 v155, v155
	v_cndmask_b32_e64 v152, 0, v152, s[62:63]
	v_cndmask_b32_e64 v153, 0, v153, s[64:65]
	v_cndmask_b32_e64 v154, 0, v154, s[66:67]
	v_cndmask_b32_e64 v155, 0, v155, s[68:69]
	v_add_f32_e32 v138, v138, v152
	v_add_f32_e32 v139, v139, v153
	v_add_f32_e32 v138, v138, v154
	v_add_f32_e32 v139, v139, v155
	v_cvt_pk_bf16_f32 v128, v152, v153
	v_cvt_pk_bf16_f32 v129, v154, v155
	v_add_f32_e32 v132, v138, v139
	v_add_u32_e32 v134, s42, v160
	v_lshlrev_b32_e32 v134, 4, v134
	v_add_u32_e32 v134, s43, v134
	v_subrev_u32_e32 v135, s15, v134
	v_lshrrev_b32_e32 v136, 4, v135
	v_add_u32_e32 v136, v136, v135
	v_mad_u32_u24 v176, v136, s79, v161
	v_lshl_add_u32 v177, v135, 2, s80
	s_and_b32 s2, s43, 3
	s_lshl_b32 s2, s2, s13
	s_lshr_b32 s3, s43, 2
	s_add_i32 s2, s2, s3
	s_lshl_b32 s2, s2, 7
	s_add_u32 s86, s20, s2
	s_addc_u32 s87, s21, 0
	s_add_i32 s2, s42, -64
	v_add_u32_e32 v136, s2, v164
	v_med3_i32 v136, v136, 0, s14
	v_lshl_add_u32 v136, v136, 9, v162
	global_load_dwordx4 v[0:3], v136, s[86:87]
	s_add_i32 s2, s42, -56
	v_add_u32_e32 v135, s2, v164
	v_med3_i32 v135, v135, 0, s14
	v_lshl_add_u32 v135, v135, 9, v162
	global_load_dwordx4 v[4:7], v135, s[86:87]
	s_add_i32 s2, s42, -48
	v_add_u32_e32 v136, s2, v164
	v_med3_i32 v136, v136, 0, s14
	v_lshl_add_u32 v136, v136, 9, v162
	global_load_dwordx4 v[8:11], v136, s[86:87]
	s_add_i32 s2, s42, -40
	v_add_u32_e32 v135, s2, v164
	v_med3_i32 v135, v135, 0, s14
	v_lshl_add_u32 v135, v135, 9, v162
	global_load_dwordx4 v[12:15], v135, s[86:87]
	ds_bpermute_b32 v142, v167, v132
	ds_write_b128 v165, v[64:67]
	ds_write_b128 v165, v[68:71] offset:1152
	ds_write_b128 v165, v[72:75] offset:2304
	ds_write_b128 v165, v[76:79] offset:3456
	s_waitcnt lgkmcnt(0)
	v_add_f32_e32 v132, v132, v142
	ds_bpermute_b32 v142, v168, v132
	ds_read_b64_tr_b16 v[236:237], v166
	ds_read_b64_tr_b16 v[238:239], v166 offset:2304
	ds_read_b64_tr_b16 v[240:241], v166 offset:32
	ds_read_b64_tr_b16 v[242:243], v166 offset:2336
	ds_read_b64_tr_b16 v[244:245], v166 offset:64
	ds_read_b64_tr_b16 v[246:247], v166 offset:2368
	ds_read_b64_tr_b16 v[248:249], v166 offset:96
	ds_read_b64_tr_b16 v[250:251], v166 offset:2400
	s_waitcnt lgkmcnt(0)
	v_add_f32_e32 v132, v132, v142
	ds_write_b128 v165, v[80:83]
	ds_write_b128 v165, v[84:87] offset:1152
	ds_write_b128 v165, v[88:91] offset:2304
	ds_write_b128 v165, v[92:95] offset:3456
	v_mfma_f32_16x16x32_bf16 v[204:207], v[236:239], v[112:115], 0
	v_mfma_f32_16x16x32_bf16 v[208:211], v[240:243], v[112:115], 0
	v_mfma_f32_16x16x32_bf16 v[212:215], v[244:247], v[112:115], 0
	v_mfma_f32_16x16x32_bf16 v[216:219], v[248:251], v[112:115], 0
	s_waitcnt lgkmcnt(0)
	ds_read_b64_tr_b16 v[236:237], v166
	ds_read_b64_tr_b16 v[238:239], v166 offset:2304
	ds_read_b64_tr_b16 v[240:241], v166 offset:32
	ds_read_b64_tr_b16 v[242:243], v166 offset:2336
	ds_read_b64_tr_b16 v[244:245], v166 offset:64
	ds_read_b64_tr_b16 v[246:247], v166 offset:2368
	ds_read_b64_tr_b16 v[248:249], v166 offset:96
	ds_read_b64_tr_b16 v[250:251], v166 offset:2400
	s_waitcnt lgkmcnt(0)
	ds_write_b128 v165, v[96:99]
	ds_write_b128 v165, v[100:103] offset:1152
	ds_write_b128 v165, v[104:107] offset:2304
	ds_write_b128 v165, v[108:111] offset:3456
	v_mfma_f32_16x16x32_bf16 v[204:207], v[236:239], v[116:119], v[204:207]
	v_mfma_f32_16x16x32_bf16 v[208:211], v[240:243], v[116:119], v[208:211]
	v_mfma_f32_16x16x32_bf16 v[212:215], v[244:247], v[116:119], v[212:215]
	v_mfma_f32_16x16x32_bf16 v[216:219], v[248:251], v[116:119], v[216:219]
	s_waitcnt lgkmcnt(0)
	ds_read_b64_tr_b16 v[236:237], v166
	ds_read_b64_tr_b16 v[238:239], v166 offset:2304
	ds_read_b64_tr_b16 v[240:241], v166 offset:32
	ds_read_b64_tr_b16 v[242:243], v166 offset:2336
	ds_read_b64_tr_b16 v[244:245], v166 offset:64
	ds_read_b64_tr_b16 v[246:247], v166 offset:2368
	ds_read_b64_tr_b16 v[248:249], v166 offset:96
	ds_read_b64_tr_b16 v[250:251], v166 offset:2400
	s_waitcnt lgkmcnt(0)
	s_waitcnt vmcnt(6)
	ds_write_b128 v165, v[16:19]
	ds_write_b128 v165, v[20:23] offset:1152
	ds_write_b128 v165, v[24:27] offset:2304
	ds_write_b128 v165, v[28:31] offset:3456
	v_mfma_f32_16x16x32_bf16 v[204:207], v[236:239], v[120:123], v[204:207]
	v_mfma_f32_16x16x32_bf16 v[208:211], v[240:243], v[120:123], v[208:211]
	v_mfma_f32_16x16x32_bf16 v[212:215], v[244:247], v[120:123], v[212:215]
	v_mfma_f32_16x16x32_bf16 v[216:219], v[248:251], v[120:123], v[216:219]
	s_waitcnt lgkmcnt(0)
	ds_read_b64_tr_b16 v[236:237], v166
	ds_read_b64_tr_b16 v[238:239], v166 offset:2304
	ds_read_b64_tr_b16 v[240:241], v166 offset:32
	ds_read_b64_tr_b16 v[242:243], v166 offset:2336
	ds_read_b64_tr_b16 v[244:245], v166 offset:64
	ds_read_b64_tr_b16 v[246:247], v166 offset:2368
	ds_read_b64_tr_b16 v[248:249], v166 offset:96
	ds_read_b64_tr_b16 v[250:251], v166 offset:2400
	s_waitcnt lgkmcnt(0)
	s_add_i32 s2, s42, -32
	v_add_u32_e32 v136, s2, v164
	v_med3_i32 v136, v136, 0, s14
	v_lshl_add_u32 v136, v136, 9, v162
	global_load_dwordx4 v[16:19], v136, s[86:87]
	s_add_i32 s2, s42, -24
	v_add_u32_e32 v135, s2, v164
	v_med3_i32 v135, v135, 0, s14
	v_lshl_add_u32 v135, v135, 9, v162
	global_load_dwordx4 v[20:23], v135, s[86:87]
	s_add_i32 s2, s42, -16
	v_add_u32_e32 v136, s2, v164
	v_med3_i32 v136, v136, 0, s14
	v_lshl_add_u32 v136, v136, 9, v162
	global_load_dwordx4 v[24:27], v136, s[86:87]
	s_add_i32 s2, s42, -8
	v_add_u32_e32 v135, s2, v164
	v_med3_i32 v135, v135, 0, s14
	v_lshl_add_u32 v135, v135, 9, v162
	global_load_dwordx4 v[28:31], v135, s[86:87]
	s_waitcnt vmcnt(8)
	ds_write_b128 v165, v[32:35]
	ds_write_b128 v165, v[36:39] offset:1152
	v_mfma_f32_16x16x32_bf16 v[204:207], v[236:239], v[124:127], v[204:207]
	v_mfma_f32_16x16x32_bf16 v[208:211], v[240:243], v[124:127], v[208:211]
	v_mfma_f32_16x16x32_bf16 v[212:215], v[244:247], v[124:127], v[212:215]
	v_mfma_f32_16x16x32_bf16 v[216:219], v[248:251], v[124:127], v[216:219]
	s_waitcnt lgkmcnt(0)
	ds_read_b64_tr_b16 v[236:237], v166
	ds_read_b64_tr_b16 v[238:239], v166 offset:2304
	ds_read_b64_tr_b16 v[240:241], v166 offset:32
	ds_read_b64_tr_b16 v[242:243], v166 offset:2336
	ds_read_b64_tr_b16 v[244:245], v166 offset:64
	ds_read_b64_tr_b16 v[246:247], v166 offset:2368
	ds_read_b64_tr_b16 v[248:249], v166 offset:96
	ds_read_b64_tr_b16 v[250:251], v166 offset:2400
	s_waitcnt lgkmcnt(0)
	s_add_i32 s2, s42, 0
	v_add_u32_e32 v136, s2, v164
	v_med3_i32 v136, v136, 0, s14
	v_lshl_add_u32 v136, v136, 9, v162
	global_load_dwordx4 v[32:35], v136, s[86:87]
	s_add_i32 s2, s42, 8
	v_add_u32_e32 v135, s2, v164
	v_med3_i32 v135, v135, 0, s14
	v_lshl_add_u32 v135, v135, 9, v162
	global_load_dwordx4 v[36:39], v135, s[86:87]
	s_add_i32 s2, s42, 16
	v_add_u32_e32 v136, s2, v164
	v_med3_i32 v136, v136, 0, s14
	v_lshl_add_u32 v136, v136, 9, v162
	global_load_dwordx4 v[40:43], v136, s[86:87]
	s_add_i32 s2, s42, 24
	v_add_u32_e32 v135, s2, v164
	v_med3_i32 v135, v135, 0, s14
	v_lshl_add_u32 v135, v135, 9, v162
	global_load_dwordx4 v[44:47], v135, s[86:87]
	v_mfma_f32_16x16x32_bf16 v[204:207], v[236:239], v[128:131], v[204:207]
	v_mfma_f32_16x16x32_bf16 v[208:211], v[240:243], v[128:131], v[208:211]
	v_mfma_f32_16x16x32_bf16 v[212:215], v[244:247], v[128:131], v[212:215]
	v_mfma_f32_16x16x32_bf16 v[216:219], v[248:251], v[128:131], v[216:219]
	s_add_i32 s2, s42, 32
	v_add_u32_e32 v136, s2, v164
	v_med3_i32 v136, v136, 0, s14
	v_lshl_add_u32 v136, v136, 9, v162
	global_load_dwordx4 v[120:123], v136, s[86:87]
	s_add_i32 s2, s42, 40
	v_add_u32_e32 v135, s2, v164
	v_med3_i32 v135, v135, 0, s14
	v_lshl_add_u32 v135, v135, 9, v162
	global_load_dwordx4 v[124:127], v135, s[86:87]
	s_add_i32 s2, s42, 48
	v_add_u32_e32 v136, s2, v164
	v_med3_i32 v136, v136, 0, s14
	v_lshl_add_u32 v136, v136, 9, v162
	global_load_dwordx4 v[192:195], v136, s[86:87]
	s_add_i32 s2, s42, 56
	v_add_u32_e32 v135, s2, v164
	v_med3_i32 v135, v135, 0, s14
	v_lshl_add_u32 v135, v135, 9, v162
	global_load_dwordx4 v[196:199], v135, s[86:87]
	s_and_b32 s2, s43, 3
	s_lshl_b32 s2, s2, s13
	s_lshr_b32 s3, s43, 2
	s_add_i32 s2, s2, s3
	s_lshl_b32 s2, s2, 7
	s_add_u32 s74, s22, s2
	s_addc_u32 s75, s23, 0
	s_add_i32 s2, s42, -64
	v_add_u32_e32 v137, s2, v164
	v_med3_i32 v137, v137, 0, s14
	v_lshl_add_u32 v137, v137, 9, v162
	global_load_dwordx4 v[64:67], v137, s[74:75]
	s_add_i32 s2, s42, -56
	v_add_u32_e32 v137, s2, v164
	v_med3_i32 v137, v137, 0, s14
	v_lshl_add_u32 v137, v137, 9, v162
	global_load_dwordx4 v[68:71], v137, s[74:75]
	s_add_i32 s2, s42, -48
	v_add_u32_e32 v137, s2, v164
	v_med3_i32 v137, v137, 0, s14
	v_lshl_add_u32 v137, v137, 9, v162
	global_load_dwordx4 v[72:75], v137, s[74:75]
	s_add_i32 s2, s42, -40
	v_add_u32_e32 v137, s2, v164
	v_med3_i32 v137, v137, 0, s14
	v_lshl_add_u32 v137, v137, 9, v162
	global_load_dwordx4 v[76:79], v137, s[74:75]
	s_and_b32 s2, s43, 3
	s_lshl_b32 s2, s2, s13
	s_lshr_b32 s3, s43, 2
	s_add_i32 s2, s2, s3
	s_lshl_b32 s2, s2, 7
	s_add_u32 s74, s22, s2
	s_addc_u32 s75, s23, 0
	s_add_i32 s2, s42, -32
	v_add_u32_e32 v137, s2, v164
	v_med3_i32 v137, v137, 0, s14
	v_lshl_add_u32 v137, v137, 9, v162
	global_load_dwordx4 v[80:83], v137, s[74:75]
	s_add_i32 s2, s42, -24
	v_add_u32_e32 v137, s2, v164
	v_med3_i32 v137, v137, 0, s14
	v_lshl_add_u32 v137, v137, 9, v162
	global_load_dwordx4 v[84:87], v137, s[74:75]
	s_add_i32 s2, s42, -16
	v_add_u32_e32 v137, s2, v164
	v_med3_i32 v137, v137, 0, s14
	v_lshl_add_u32 v137, v137, 9, v162
	global_load_dwordx4 v[88:91], v137, s[74:75]
	s_add_i32 s2, s42, -8
	v_add_u32_e32 v137, s2, v164
	v_med3_i32 v137, v137, 0, s14
	v_lshl_add_u32 v137, v137, 9, v162
	global_load_dwordx4 v[92:95], v137, s[74:75]
	s_and_b32 s2, s43, 3
	s_lshl_b32 s2, s2, s13
	s_lshr_b32 s3, s43, 2
	s_add_i32 s2, s2, s3
	s_lshl_b32 s2, s2, 7
	s_add_u32 s74, s22, s2
	s_addc_u32 s75, s23, 0
	s_add_i32 s2, s42, 0
	v_add_u32_e32 v137, s2, v164
	v_med3_i32 v137, v137, 0, s14
	v_lshl_add_u32 v137, v137, 9, v162
	global_load_dwordx4 v[96:99], v137, s[74:75]
	s_add_i32 s2, s42, 8
	v_add_u32_e32 v137, s2, v164
	v_med3_i32 v137, v137, 0, s14
	v_lshl_add_u32 v137, v137, 9, v162
	global_load_dwordx4 v[100:103], v137, s[74:75]
	s_add_i32 s2, s42, 16
	v_add_u32_e32 v137, s2, v164
	v_med3_i32 v137, v137, 0, s14
	v_lshl_add_u32 v137, v137, 9, v162
	global_load_dwordx4 v[104:107], v137, s[74:75]
	s_add_i32 s2, s42, 24
	v_add_u32_e32 v137, s2, v164
	v_med3_i32 v137, v137, 0, s14
	v_lshl_add_u32 v137, v137, 9, v162
	global_load_dwordx4 v[108:111], v137, s[74:75]
	s_waitcnt lgkmcnt(0)
	s_barrier
	ds_read_b128 v[236:239], v173 offset:0
	ds_read_b128 v[240:243], v173 offset:64
	ds_read_b128 v[244:247], v173 offset:128
	ds_read_b128 v[248:251], v173 offset:192
	ds_read_b32 v142, v174 offset:0
	s_waitcnt lgkmcnt(0)
	v_add_f32_e32 v204, v236, v204
	v_add_f32_e32 v205, v237, v205
	v_add_f32_e32 v206, v238, v206
	v_add_f32_e32 v207, v239, v207
	v_add_f32_e32 v208, v240, v208
	v_add_f32_e32 v209, v241, v209
	v_add_f32_e32 v210, v242, v210
	v_add_f32_e32 v211, v243, v211
	v_add_f32_e32 v212, v244, v212
	v_add_f32_e32 v213, v245, v213
	v_add_f32_e32 v214, v246, v214
	v_add_f32_e32 v215, v247, v215
	v_add_f32_e32 v216, v248, v216
	v_add_f32_e32 v217, v249, v217
	v_add_f32_e32 v218, v250, v218
	v_add_f32_e32 v219, v251, v219
	v_add_f32_e32 v132, v142, v132
	ds_write_b128 v173, v[204:207] offset:0
	ds_write_b128 v173, v[208:211] offset:64
	ds_write_b128 v173, v[212:215] offset:128
	ds_write_b128 v173, v[216:219] offset:192
	ds_write_b32 v174, v132 offset:0
	s_mov_b32 s40, s42
	s_mov_b32 s41, s43
	v_mov_b32_e32 v173, v176
	v_mov_b32_e32 v174, v177
	s_lshr_b32 s44, s33, 4
	s_add_i32 s45, s10, s8
	s_cmp_lt_u32 s45, 0x800
	s_cbranch_scc1 .Latt_newunit
	s_mov_b32 s37, 1
	s_branch .Latt_ud_done
